# GEMM MFMA phase head: s_setprio 1 moved before the barrier, redundant lgkmcnt(0) after the barrier removed (on top of k-inner order)
# speedup vs baseline: 1.0048x; 1.0002x over previous
; #define PG8_STAGE(bufoff, gbase, voff) do { _Pragma("unroll") for (int _i = 0; _i < 2; ++_i) \
;         __builtin_amdgcn_global_load_lds((const unsigned*)((const char*)(gbase) + (voff)[_i]), (LAS unsigned*)(lds + (bufoff) + ldsw + _i * 8192), 16, 0, 0); } while (0)
; #define PG8_LDA(dst, b, h) do { _Pragma("unroll") for (int m = 0; m < 4; ++m) _Pragma("unroll") for (int k = 0; k < 2; ++k) dst[m][k] = *(const LAS bf16x8*)(lds + PG8_SA(b, h) + aoff + m * 2048 + k * 1024); } while (0)
; #define PG8_LDB(dst, b, h) do { _Pragma("unroll") for (int n = 0; n < 2; ++n) _Pragma("unroll") for (int k = 0; k < 2; ++k) dst[n][k] = *(const LAS bf16x8*)(lds + PG8_SB(b, h) + boff + n * 2048 + k * 1024); } while (0)
; template <class Epi, class Sched, bool ALIGN_EPI = false, bool SP2 = false>
; __device__ __forceinline__ void gemm_phase(LAS unsigned char* lds, const Gemm g, const Sched& S, const Epi& E) {
;     ...
;         for (int t = 0; t < nt; t += 2) {
;             const bool last = (t == nt - 2);
;             const char* a1 = cA + (size_t)(t + 1) * kstep;
;             const char* a2 = last ? nA : cA + (size_t)(t + 2) * kstep; const char* b2 = last ? nB : cB + (size_t)(t + 2) * kstep;
;             const char* a3 = a2 + kstep; const char* b3 = b2 + kstep;
;             if (last && has_next) S.a_ready(nxt);
;             if constexpr (SP2) {
;             PG8_LDB(B0, 0, 0); PG8_LDB(B1, 0, 1); PG8_SCHED; PG8_LDA(At, 0, 0); PG8_STAGE(PG8_SA(1, 1), a1 + hstep, voffA);
;             PG8_WAIT_V(8); PG8_WAIT_L(0); PG8_BAR; PG8_MMA(0, 0, At, B0); PG8_MMA(0, 1, At, B1); PG8_BAR; PG8_SCHED;
;             PG8_LDA(At, 0, 1); PG8_STAGE(PG8_SB(0, 0), b2, voffB); PG8_STAGE(PG8_SB(0, 1), b2 + hstep, voffB); PG8_STAGE(PG8_SA(0, 0), a2, voffA);
;             PG8_WAIT_V(8); PG8_WAIT_L(0); PG8_BAR; PG8_MMA(1, 0, At, B0); PG8_MMA(1, 1, At, B1); PG8_BAR; PG8_SCHED;
;             PG8_LDB(B0, 1, 0); PG8_LDB(B1, 1, 1); PG8_SCHED; PG8_LDA(At, 1, 0); PG8_STAGE(PG8_SA(0, 1), a2 + hstep, voffA);
;             PG8_WAIT_V(8); PG8_WAIT_L(0); PG8_BAR; PG8_MMA(0, 0, At, B0); PG8_MMA(0, 1, At, B1); PG8_BAR; PG8_SCHED;
;             PG8_LDA(At, 1, 1); PG8_STAGE(PG8_SB(1, 0), b3, voffB); PG8_STAGE(PG8_SB(1, 1), b3 + hstep, voffB); PG8_STAGE(PG8_SA(1, 0), a3, voffA);
;             PG8_WAIT_V(8); PG8_WAIT_L(0); PG8_BAR; PG8_MMA(1, 0, At, B0); PG8_MMA(1, 1, At, B1); PG8_BAR; PG8_SCHED;
.LBB0_173:
	s_add_u32 s26, s24, 0xfff80080
	s_addc_u32 s27, s25, -1
	s_add_i32 s45, 0, 0x10000
	s_cmp_eq_u32 s44, 28
	s_cselect_b32 s29, s7, s27
	s_cselect_b32 s28, s8, s26
	v_add_u32_e32 v140, s45, v145
	s_cselect_b32 s27, s17, s43
	s_cselect_b32 s26, s19, s35
	s_add_i32 s47, 0, 0x14000
	ds_read_b128 v[150:153], v140
	ds_read_b128 v[154:157], v140 offset:1024
	ds_read_b128 v[158:161], v140 offset:2048
	ds_read_b128 v[162:165], v140 offset:3072
	v_add_u32_e32 v140, s47, v145
	ds_read_b128 v[166:169], v140
	ds_read_b128 v[170:173], v140 offset:1024
	ds_read_b128 v[174:177], v140 offset:2048
	ds_read_b128 v[178:181], v140 offset:3072
	v_lshl_add_u64 v[140:141], s[24:25], 0, v[136:137]
	s_add_i32 m0, s30, 0xc000
	ds_read_b128 v[182:185], v149
	ds_read_b128 v[194:197], v149 offset:1024
	ds_read_b128 v[198:201], v149 offset:2048
	ds_read_b128 v[202:205], v149 offset:3072
	ds_read_b128 v[206:209], v149 offset:4096
	ds_read_b128 v[210:213], v149 offset:5120
	ds_read_b128 v[214:217], v149 offset:6144
	ds_read_b128 v[218:221], v149 offset:7168
	global_load_lds_dwordx4 v[140:141], off
	v_lshl_add_u64 v[140:141], s[24:25], 0, v[138:139]
	s_add_i32 m0, s30, 0xe000
	s_nop 0
	global_load_lds_dwordx4 v[140:141], off
	s_waitcnt vmcnt(8)
	s_waitcnt lgkmcnt(0)
	s_setprio 1
	s_barrier
	v_mfma_f32_16x16x32_bf16 v[126:129], v[150:153], v[182:185], v[126:129]
	v_mfma_f32_16x16x32_bf16 v[126:129], v[154:157], v[194:197], v[126:129]
	v_mfma_f32_16x16x32_bf16 v[122:125], v[158:161], v[182:185], v[122:125]
	v_mfma_f32_16x16x32_bf16 v[122:125], v[162:165], v[194:197], v[122:125]
	v_mfma_f32_16x16x32_bf16 v[106:109], v[158:161], v[198:201], v[106:109]
	v_mfma_f32_16x16x32_bf16 v[106:109], v[162:165], v[202:205], v[106:109]
	v_mfma_f32_16x16x32_bf16 v[110:113], v[150:153], v[198:201], v[110:113]
	v_mfma_f32_16x16x32_bf16 v[110:113], v[154:157], v[202:205], v[110:113]
	v_mfma_f32_16x16x32_bf16 v[94:97], v[150:153], v[206:209], v[94:97]
	v_mfma_f32_16x16x32_bf16 v[94:97], v[154:157], v[210:213], v[94:97]
	v_mfma_f32_16x16x32_bf16 v[90:93], v[158:161], v[206:209], v[90:93]
	v_mfma_f32_16x16x32_bf16 v[90:93], v[162:165], v[210:213], v[90:93]
	v_mfma_f32_16x16x32_bf16 v[74:77], v[158:161], v[214:217], v[74:77]
	v_mfma_f32_16x16x32_bf16 v[74:77], v[162:165], v[218:221], v[74:77]
	v_mfma_f32_16x16x32_bf16 v[78:81], v[150:153], v[214:217], v[78:81]
	v_mfma_f32_16x16x32_bf16 v[78:81], v[154:157], v[218:221], v[78:81]
	s_setprio 0
	s_setprio 1
	v_mfma_f32_16x16x32_bf16 v[118:121], v[166:169], v[182:185], v[118:121]
	v_mfma_f32_16x16x32_bf16 v[118:121], v[170:173], v[194:197], v[118:121]
	v_mfma_f32_16x16x32_bf16 v[114:117], v[174:177], v[182:185], v[114:117]
	v_mfma_f32_16x16x32_bf16 v[114:117], v[178:181], v[194:197], v[114:117]
	v_mfma_f32_16x16x32_bf16 v[98:101], v[174:177], v[198:201], v[98:101]
	v_mfma_f32_16x16x32_bf16 v[98:101], v[178:181], v[202:205], v[98:101]
	v_mfma_f32_16x16x32_bf16 v[102:105], v[166:169], v[198:201], v[102:105]
	v_mfma_f32_16x16x32_bf16 v[102:105], v[170:173], v[202:205], v[102:105]
	v_mfma_f32_16x16x32_bf16 v[86:89], v[166:169], v[206:209], v[86:89]
	v_mfma_f32_16x16x32_bf16 v[86:89], v[170:173], v[210:213], v[86:89]
	v_mfma_f32_16x16x32_bf16 v[82:85], v[174:177], v[206:209], v[82:85]
	v_mfma_f32_16x16x32_bf16 v[82:85], v[178:181], v[210:213], v[82:85]
	v_mfma_f32_16x16x32_bf16 v[66:69], v[174:177], v[214:217], v[66:69]
	v_mfma_f32_16x16x32_bf16 v[66:69], v[178:181], v[218:221], v[66:69]
	v_mfma_f32_16x16x32_bf16 v[70:73], v[166:169], v[214:217], v[70:73]
	v_mfma_f32_16x16x32_bf16 v[70:73], v[170:173], v[218:221], v[70:73]
	s_setprio 0
	s_barrier
	s_add_i32 s45, s45, s9
	v_lshl_add_u64 v[140:141], s[26:27], 0, v[0:1]
	s_mov_b32 m0, s45
	ds_read_b128 v[182:185], v149 offset:16384
	ds_read_b128 v[194:197], v149 offset:17408
	ds_read_b128 v[198:201], v149 offset:18432
	ds_read_b128 v[202:205], v149 offset:19456
	ds_read_b128 v[206:209], v149 offset:20480
	ds_read_b128 v[210:213], v149 offset:21504
	ds_read_b128 v[214:217], v149 offset:22528
	ds_read_b128 v[218:221], v149 offset:23552
	global_load_lds_dwordx4 v[140:141], off
	s_add_i32 m0, s45, 0x2000
	s_add_u32 s48, s26, 0x80000
	v_lshl_add_u64 v[186:187], s[26:27], 0, v[130:131]
	s_addc_u32 s49, s27, 0
	s_add_i32 s45, s47, s9
	global_load_lds_dwordx4 v[186:187], off
	v_lshl_add_u64 v[188:189], s[48:49], 0, v[0:1]
	s_mov_b32 m0, s45
	v_lshl_add_u64 v[190:191], s[28:29], 0, v[132:133]
	global_load_lds_dwordx4 v[188:189], off
	v_lshl_add_u64 v[188:189], s[48:49], 0, v[130:131]
	s_add_i32 m0, s45, 0x2000
	s_nop 0
	global_load_lds_dwordx4 v[188:189], off
	v_lshl_add_u64 v[188:189], s[28:29], 0, v[134:135]
	s_mov_b32 m0, s30
	s_nop 0
	global_load_lds_dwordx4 v[188:189], off
	s_mov_b32 m0, s31
	s_nop 0
	global_load_lds_dwordx4 v[190:191], off
	s_waitcnt vmcnt(8)
	s_waitcnt lgkmcnt(0)
	s_setprio 1
	s_barrier
; #define PG8_STAGE(bufoff, gbase, voff) do { _Pragma("unroll") for (int _i = 0; _i < 2; ++_i) \
;         __builtin_amdgcn_global_load_lds((const unsigned*)((const char*)(gbase) + (voff)[_i]), (LAS unsigned*)(lds + (bufoff) + ldsw + _i * 8192), 16, 0, 0); } while (0)
; #define PG8_LDA(dst, b, h) do { _Pragma("unroll") for (int m = 0; m < 4; ++m) _Pragma("unroll") for (int k = 0; k < 2; ++k) dst[m][k] = *(const LAS bf16x8*)(lds + PG8_SA(b, h) + aoff + m * 2048 + k * 1024); } while (0)
; #define PG8_LDB(dst, b, h) do { _Pragma("unroll") for (int n = 0; n < 2; ++n) _Pragma("unroll") for (int k = 0; k < 2; ++k) dst[n][k] = *(const LAS bf16x8*)(lds + PG8_SB(b, h) + boff + n * 2048 + k * 1024); } while (0)
; template <class Epi, class Sched, bool ALIGN_EPI = false, bool SP2 = false>
; __device__ __forceinline__ void gemm_phase(LAS unsigned char* lds, const Gemm g, const Sched& S, const Epi& E) {
;     ...
;         for (int t = 0; t < nt; t += 2) {
;             const bool last = (t == nt - 2);
;             const char* a1 = cA + (size_t)(t + 1) * kstep;
;             const char* a2 = last ? nA : cA + (size_t)(t + 2) * kstep; const char* b2 = last ? nB : cB + (size_t)(t + 2) * kstep;
;             const char* a3 = a2 + kstep; const char* b3 = b2 + kstep;
;             if (last && has_next) S.a_ready(nxt);
;             if constexpr (SP2) {
;             PG8_LDB(B0, 0, 0); PG8_LDB(B1, 0, 1); PG8_SCHED; PG8_LDA(At, 0, 0); PG8_STAGE(PG8_SA(1, 1), a1 + hstep, voffA);
;             PG8_WAIT_V(8); PG8_WAIT_L(0); PG8_BAR; PG8_MMA(0, 0, At, B0); PG8_MMA(0, 1, At, B1); PG8_BAR; PG8_SCHED;
;             PG8_LDA(At, 0, 1); PG8_STAGE(PG8_SB(0, 0), b2, voffB); PG8_STAGE(PG8_SB(0, 1), b2 + hstep, voffB); PG8_STAGE(PG8_SA(0, 0), a2, voffA);
;             PG8_WAIT_V(8); PG8_WAIT_L(0); PG8_BAR; PG8_MMA(1, 0, At, B0); PG8_MMA(1, 1, At, B1); PG8_BAR; PG8_SCHED;
;             PG8_LDB(B0, 1, 0); PG8_LDB(B1, 1, 1); PG8_SCHED; PG8_LDA(At, 1, 0); PG8_STAGE(PG8_SA(0, 1), a2 + hstep, voffA);
;             PG8_WAIT_V(8); PG8_WAIT_L(0); PG8_BAR; PG8_MMA(0, 0, At, B0); PG8_MMA(0, 1, At, B1); PG8_BAR; PG8_SCHED;
;             PG8_LDA(At, 1, 1); PG8_STAGE(PG8_SB(1, 0), b3, voffB); PG8_STAGE(PG8_SB(1, 1), b3 + hstep, voffB); PG8_STAGE(PG8_SA(1, 0), a3, voffA);
;             PG8_WAIT_V(8); PG8_WAIT_L(0); PG8_BAR; PG8_MMA(1, 0, At, B0); PG8_MMA(1, 1, At, B1); PG8_BAR; PG8_SCHED;
	v_mfma_f32_16x16x32_bf16 v[62:65], v[150:153], v[182:185], v[62:65]
	v_mfma_f32_16x16x32_bf16 v[62:65], v[154:157], v[194:197], v[62:65]
	v_mfma_f32_16x16x32_bf16 v[58:61], v[158:161], v[182:185], v[58:61]
	v_mfma_f32_16x16x32_bf16 v[58:61], v[162:165], v[194:197], v[58:61]
	v_mfma_f32_16x16x32_bf16 v[42:45], v[158:161], v[198:201], v[42:45]
	v_mfma_f32_16x16x32_bf16 v[42:45], v[162:165], v[202:205], v[42:45]
	v_mfma_f32_16x16x32_bf16 v[46:49], v[150:153], v[198:201], v[46:49]
	v_mfma_f32_16x16x32_bf16 v[46:49], v[154:157], v[202:205], v[46:49]
	v_mfma_f32_16x16x32_bf16 v[30:33], v[150:153], v[206:209], v[30:33]
	v_mfma_f32_16x16x32_bf16 v[30:33], v[154:157], v[210:213], v[30:33]
	v_mfma_f32_16x16x32_bf16 v[26:29], v[158:161], v[206:209], v[26:29]
	v_mfma_f32_16x16x32_bf16 v[26:29], v[162:165], v[210:213], v[26:29]
	v_mfma_f32_16x16x32_bf16 v[10:13], v[158:161], v[214:217], v[10:13]
	v_mfma_f32_16x16x32_bf16 v[10:13], v[162:165], v[218:221], v[10:13]
	v_mfma_f32_16x16x32_bf16 v[14:17], v[150:153], v[214:217], v[14:17]
	v_mfma_f32_16x16x32_bf16 v[14:17], v[154:157], v[218:221], v[14:17]
	s_setprio 0
	s_setprio 1
	v_mfma_f32_16x16x32_bf16 v[54:57], v[166:169], v[182:185], v[54:57]
	v_mfma_f32_16x16x32_bf16 v[54:57], v[170:173], v[194:197], v[54:57]
	v_mfma_f32_16x16x32_bf16 v[50:53], v[174:177], v[182:185], v[50:53]
	v_mfma_f32_16x16x32_bf16 v[50:53], v[178:181], v[194:197], v[50:53]
	v_mfma_f32_16x16x32_bf16 v[34:37], v[174:177], v[198:201], v[34:37]
	v_mfma_f32_16x16x32_bf16 v[34:37], v[178:181], v[202:205], v[34:37]
	v_mfma_f32_16x16x32_bf16 v[38:41], v[166:169], v[198:201], v[38:41]
	v_mfma_f32_16x16x32_bf16 v[38:41], v[170:173], v[202:205], v[38:41]
	v_mfma_f32_16x16x32_bf16 v[22:25], v[166:169], v[206:209], v[22:25]
	v_mfma_f32_16x16x32_bf16 v[22:25], v[170:173], v[210:213], v[22:25]
	v_mfma_f32_16x16x32_bf16 v[18:21], v[174:177], v[206:209], v[18:21]
	v_mfma_f32_16x16x32_bf16 v[18:21], v[178:181], v[210:213], v[18:21]
	v_mfma_f32_16x16x32_bf16 v[2:5], v[174:177], v[214:217], v[2:5]
	v_mfma_f32_16x16x32_bf16 v[2:5], v[178:181], v[218:221], v[2:5]
	v_mfma_f32_16x16x32_bf16 v[6:9], v[166:169], v[214:217], v[6:9]
	v_mfma_f32_16x16x32_bf16 v[6:9], v[170:173], v[218:221], v[6:9]
	s_setprio 0
	s_barrier
	s_add_i32 s45, 0, 0x18000
	v_add_u32_e32 v142, s45, v145
	s_add_i32 s47, 0, 0x1c000
	ds_read_b128 v[150:153], v142
	ds_read_b128 v[154:157], v142 offset:1024
	ds_read_b128 v[158:161], v142 offset:2048
	ds_read_b128 v[162:165], v142 offset:3072
	v_add_u32_e32 v142, s47, v145
	ds_read_b128 v[166:169], v142
	ds_read_b128 v[170:173], v142 offset:1024
	ds_read_b128 v[174:177], v142 offset:2048
	ds_read_b128 v[178:181], v142 offset:3072
	s_add_u32 s28, s28, 0x80000
	s_addc_u32 s29, s29, 0
	s_mov_b32 m0, s38
	v_lshl_add_u64 v[192:193], s[28:29], 0, v[134:135]
	ds_read_b128 v[182:185], v149 offset:32768
	ds_read_b128 v[194:197], v149 offset:33792
	ds_read_b128 v[198:201], v149 offset:34816
	ds_read_b128 v[202:205], v149 offset:35840
	ds_read_b128 v[206:209], v149 offset:36864
	ds_read_b128 v[210:213], v149 offset:37888
	ds_read_b128 v[214:217], v149 offset:38912
	ds_read_b128 v[218:221], v149 offset:39936
	global_load_lds_dwordx4 v[192:193], off
	v_lshl_add_u64 v[192:193], s[28:29], 0, v[132:133]
	s_mov_b32 m0, s39
	s_nop 0
	global_load_lds_dwordx4 v[192:193], off
	s_waitcnt vmcnt(8)
	s_waitcnt lgkmcnt(0)
	s_setprio 1
	s_barrier
	v_mfma_f32_16x16x32_bf16 v[126:129], v[150:153], v[182:185], v[126:129]
	v_mfma_f32_16x16x32_bf16 v[126:129], v[154:157], v[194:197], v[126:129]
	v_mfma_f32_16x16x32_bf16 v[122:125], v[158:161], v[182:185], v[122:125]
	v_mfma_f32_16x16x32_bf16 v[122:125], v[162:165], v[194:197], v[122:125]
	v_mfma_f32_16x16x32_bf16 v[106:109], v[158:161], v[198:201], v[106:109]
	v_mfma_f32_16x16x32_bf16 v[106:109], v[162:165], v[202:205], v[106:109]
	v_mfma_f32_16x16x32_bf16 v[110:113], v[150:153], v[198:201], v[110:113]
	v_mfma_f32_16x16x32_bf16 v[110:113], v[154:157], v[202:205], v[110:113]
	v_mfma_f32_16x16x32_bf16 v[94:97], v[150:153], v[206:209], v[94:97]
	v_mfma_f32_16x16x32_bf16 v[94:97], v[154:157], v[210:213], v[94:97]
	v_mfma_f32_16x16x32_bf16 v[90:93], v[158:161], v[206:209], v[90:93]
	v_mfma_f32_16x16x32_bf16 v[90:93], v[162:165], v[210:213], v[90:93]
	v_mfma_f32_16x16x32_bf16 v[74:77], v[158:161], v[214:217], v[74:77]
	v_mfma_f32_16x16x32_bf16 v[74:77], v[162:165], v[218:221], v[74:77]
	v_mfma_f32_16x16x32_bf16 v[78:81], v[150:153], v[214:217], v[78:81]
	v_mfma_f32_16x16x32_bf16 v[78:81], v[154:157], v[218:221], v[78:81]
	s_setprio 0
	s_setprio 1
	v_mfma_f32_16x16x32_bf16 v[118:121], v[166:169], v[182:185], v[118:121]
	v_mfma_f32_16x16x32_bf16 v[118:121], v[170:173], v[194:197], v[118:121]
	v_mfma_f32_16x16x32_bf16 v[114:117], v[174:177], v[182:185], v[114:117]
	v_mfma_f32_16x16x32_bf16 v[114:117], v[178:181], v[194:197], v[114:117]
	v_mfma_f32_16x16x32_bf16 v[98:101], v[174:177], v[198:201], v[98:101]
	v_mfma_f32_16x16x32_bf16 v[98:101], v[178:181], v[202:205], v[98:101]
	v_mfma_f32_16x16x32_bf16 v[102:105], v[166:169], v[198:201], v[102:105]
	v_mfma_f32_16x16x32_bf16 v[102:105], v[170:173], v[202:205], v[102:105]
	v_mfma_f32_16x16x32_bf16 v[86:89], v[166:169], v[206:209], v[86:89]
	v_mfma_f32_16x16x32_bf16 v[86:89], v[170:173], v[210:213], v[86:89]
	v_mfma_f32_16x16x32_bf16 v[82:85], v[174:177], v[206:209], v[82:85]
	v_mfma_f32_16x16x32_bf16 v[82:85], v[178:181], v[210:213], v[82:85]
	v_mfma_f32_16x16x32_bf16 v[66:69], v[174:177], v[214:217], v[66:69]
	v_mfma_f32_16x16x32_bf16 v[66:69], v[178:181], v[218:221], v[66:69]
	v_mfma_f32_16x16x32_bf16 v[70:73], v[166:169], v[214:217], v[70:73]
	v_mfma_f32_16x16x32_bf16 v[70:73], v[170:173], v[218:221], v[70:73]
	s_setprio 0
	s_barrier
; #define PG8_STAGE(bufoff, gbase, voff) do { _Pragma("unroll") for (int _i = 0; _i < 2; ++_i) \
;         __builtin_amdgcn_global_load_lds((const unsigned*)((const char*)(gbase) + (voff)[_i]), (LAS unsigned*)(lds + (bufoff) + ldsw + _i * 8192), 16, 0, 0); } while (0)
; #define PG8_LDA(dst, b, h) do { _Pragma("unroll") for (int m = 0; m < 4; ++m) _Pragma("unroll") for (int k = 0; k < 2; ++k) dst[m][k] = *(const LAS bf16x8*)(lds + PG8_SA(b, h) + aoff + m * 2048 + k * 1024); } while (0)
; #define PG8_LDB(dst, b, h) do { _Pragma("unroll") for (int n = 0; n < 2; ++n) _Pragma("unroll") for (int k = 0; k < 2; ++k) dst[n][k] = *(const LAS bf16x8*)(lds + PG8_SB(b, h) + boff + n * 2048 + k * 1024); } while (0)
; template <class Epi, class Sched, bool ALIGN_EPI = false, bool SP2 = false>
; __device__ __forceinline__ void gemm_phase(LAS unsigned char* lds, const Gemm g, const Sched& S, const Epi& E) {
;     ...
;         for (int t = 0; t < nt; t += 2) {
;             const bool last = (t == nt - 2);
;             const char* a1 = cA + (size_t)(t + 1) * kstep;
;             const char* a2 = last ? nA : cA + (size_t)(t + 2) * kstep; const char* b2 = last ? nB : cB + (size_t)(t + 2) * kstep;
;             const char* a3 = a2 + kstep; const char* b3 = b2 + kstep;
;             if (last && has_next) S.a_ready(nxt);
;             if constexpr (SP2) {
;             PG8_LDB(B0, 0, 0); PG8_LDB(B1, 0, 1); PG8_SCHED; PG8_LDA(At, 0, 0); PG8_STAGE(PG8_SA(1, 1), a1 + hstep, voffA);
;             PG8_WAIT_V(8); PG8_WAIT_L(0); PG8_BAR; PG8_MMA(0, 0, At, B0); PG8_MMA(0, 1, At, B1); PG8_BAR; PG8_SCHED;
;             PG8_LDA(At, 0, 1); PG8_STAGE(PG8_SB(0, 0), b2, voffB); PG8_STAGE(PG8_SB(0, 1), b2 + hstep, voffB); PG8_STAGE(PG8_SA(0, 0), a2, voffA);
;             PG8_WAIT_V(8); PG8_WAIT_L(0); PG8_BAR; PG8_MMA(1, 0, At, B0); PG8_MMA(1, 1, At, B1); PG8_BAR; PG8_SCHED;
;             PG8_LDB(B0, 1, 0); PG8_LDB(B1, 1, 1); PG8_SCHED; PG8_LDA(At, 1, 0); PG8_STAGE(PG8_SA(0, 1), a2 + hstep, voffA);
;             PG8_WAIT_V(8); PG8_WAIT_L(0); PG8_BAR; PG8_MMA(0, 0, At, B0); PG8_MMA(0, 1, At, B1); PG8_BAR; PG8_SCHED;
;             PG8_LDA(At, 1, 1); PG8_STAGE(PG8_SB(1, 0), b3, voffB); PG8_STAGE(PG8_SB(1, 1), b3 + hstep, voffB); PG8_STAGE(PG8_SA(1, 0), a3, voffA);
;             PG8_WAIT_V(8); PG8_WAIT_L(0); PG8_BAR; PG8_MMA(1, 0, At, B0); PG8_MMA(1, 1, At, B1); PG8_BAR; PG8_SCHED;
	s_add_i32 s28, s45, s9
	v_lshl_add_u64 v[140:141], v[140:141], 0, s[12:13]
	s_mov_b32 m0, s28
	ds_read_b128 v[182:185], v149 offset:49152
	ds_read_b128 v[194:197], v149 offset:50176
	ds_read_b128 v[198:201], v149 offset:51200
	ds_read_b128 v[202:205], v149 offset:52224
	ds_read_b128 v[206:209], v149 offset:53248
	ds_read_b128 v[210:213], v149 offset:54272
	ds_read_b128 v[214:217], v149 offset:55296
	ds_read_b128 v[218:221], v149 offset:56320
	global_load_lds_dwordx4 v[140:141], off
	s_add_i32 m0, s28, 0x2000
	s_add_u32 s26, s26, 0x80080
	v_lshl_add_u64 v[140:141], v[186:187], 0, s[12:13]
	s_addc_u32 s27, s27, 0
	s_add_i32 s28, s47, s9
	global_load_lds_dwordx4 v[140:141], off
	v_lshl_add_u64 v[140:141], s[26:27], 0, v[0:1]
	s_mov_b32 m0, s28
	s_nop 0
	global_load_lds_dwordx4 v[140:141], off
	v_lshl_add_u64 v[140:141], s[26:27], 0, v[130:131]
	s_add_i32 m0, s28, 0x2000
	s_nop 0
	global_load_lds_dwordx4 v[140:141], off
	v_lshl_add_u64 v[140:141], v[188:189], 0, s[12:13]
	s_mov_b32 m0, s40
	s_nop 0
	global_load_lds_dwordx4 v[140:141], off
	v_lshl_add_u64 v[140:141], v[190:191], 0, s[12:13]
	s_mov_b32 m0, s41
	s_nop 0
	global_load_lds_dwordx4 v[140:141], off
	s_waitcnt vmcnt(8)
	s_waitcnt lgkmcnt(0)
	s_setprio 1
	s_barrier
	v_mfma_f32_16x16x32_bf16 v[62:65], v[150:153], v[182:185], v[62:65]
	v_mfma_f32_16x16x32_bf16 v[62:65], v[154:157], v[194:197], v[62:65]
	v_mfma_f32_16x16x32_bf16 v[58:61], v[158:161], v[182:185], v[58:61]
	v_mfma_f32_16x16x32_bf16 v[58:61], v[162:165], v[194:197], v[58:61]
	v_mfma_f32_16x16x32_bf16 v[42:45], v[158:161], v[198:201], v[42:45]
	v_mfma_f32_16x16x32_bf16 v[42:45], v[162:165], v[202:205], v[42:45]
	v_mfma_f32_16x16x32_bf16 v[46:49], v[150:153], v[198:201], v[46:49]
	v_mfma_f32_16x16x32_bf16 v[46:49], v[154:157], v[202:205], v[46:49]
	v_mfma_f32_16x16x32_bf16 v[30:33], v[150:153], v[206:209], v[30:33]
	v_mfma_f32_16x16x32_bf16 v[30:33], v[154:157], v[210:213], v[30:33]
	v_mfma_f32_16x16x32_bf16 v[26:29], v[158:161], v[206:209], v[26:29]
	v_mfma_f32_16x16x32_bf16 v[26:29], v[162:165], v[210:213], v[26:29]
	v_mfma_f32_16x16x32_bf16 v[10:13], v[158:161], v[214:217], v[10:13]
	v_mfma_f32_16x16x32_bf16 v[10:13], v[162:165], v[218:221], v[10:13]
	v_mfma_f32_16x16x32_bf16 v[14:17], v[150:153], v[214:217], v[14:17]
	v_mfma_f32_16x16x32_bf16 v[14:17], v[154:157], v[218:221], v[14:17]
	s_setprio 0
	s_setprio 1
	v_mfma_f32_16x16x32_bf16 v[54:57], v[166:169], v[182:185], v[54:57]
	v_mfma_f32_16x16x32_bf16 v[54:57], v[170:173], v[194:197], v[54:57]
	v_mfma_f32_16x16x32_bf16 v[50:53], v[174:177], v[182:185], v[50:53]
	v_mfma_f32_16x16x32_bf16 v[50:53], v[178:181], v[194:197], v[50:53]
	v_mfma_f32_16x16x32_bf16 v[34:37], v[174:177], v[198:201], v[34:37]
	v_mfma_f32_16x16x32_bf16 v[34:37], v[178:181], v[202:205], v[34:37]
	v_mfma_f32_16x16x32_bf16 v[38:41], v[166:169], v[198:201], v[38:41]
	v_mfma_f32_16x16x32_bf16 v[38:41], v[170:173], v[202:205], v[38:41]
	v_mfma_f32_16x16x32_bf16 v[22:25], v[166:169], v[206:209], v[22:25]
	v_mfma_f32_16x16x32_bf16 v[22:25], v[170:173], v[210:213], v[22:25]
	v_mfma_f32_16x16x32_bf16 v[18:21], v[174:177], v[206:209], v[18:21]
	v_mfma_f32_16x16x32_bf16 v[18:21], v[178:181], v[210:213], v[18:21]
	v_mfma_f32_16x16x32_bf16 v[2:5], v[174:177], v[214:217], v[2:5]
	v_mfma_f32_16x16x32_bf16 v[2:5], v[178:181], v[218:221], v[2:5]
	v_mfma_f32_16x16x32_bf16 v[6:9], v[166:169], v[214:217], v[6:9]
	v_mfma_f32_16x16x32_bf16 v[6:9], v[170:173], v[218:221], v[6:9]
	s_setprio 0
	s_barrier
	s_add_i32 s44, s44, 2
	s_add_u32 s24, s24, 0x100
	s_addc_u32 s25, s25, 0
	s_add_u32 s35, s35, 0x100
	s_addc_u32 s43, s43, 0
	s_cmp_gt_u32 s44, 29
	s_cbranch_scc0 .LBB0_173
	s_and_b64 vcc, exec, s[4:5]
	s_cbranch_vccz .LBB0_176
	s_barrier

; #define PG8_STAGE(bufoff, gbase, voff) do { _Pragma("unroll") for (int _i = 0; _i < 2; ++_i) \
;         __builtin_amdgcn_global_load_lds((const unsigned*)((const char*)(gbase) + (voff)[_i]), (LAS unsigned*)(lds + (bufoff) + ldsw + _i * 8192), 16, 0, 0); } while (0)
; #define PG8_LDA(dst, b, h) do { _Pragma("unroll") for (int m = 0; m < 4; ++m) _Pragma("unroll") for (int k = 0; k < 2; ++k) dst[m][k] = *(const LAS bf16x8*)(lds + PG8_SA(b, h) + aoff + m * 2048 + k * 1024); } while (0)
; #define PG8_LDB(dst, b, h) do { _Pragma("unroll") for (int n = 0; n < 2; ++n) _Pragma("unroll") for (int k = 0; k < 2; ++k) dst[n][k] = *(const LAS bf16x8*)(lds + PG8_SB(b, h) + boff + n * 2048 + k * 1024); } while (0)
; template <class Epi, class Sched, bool ALIGN_EPI = false, bool SP2 = false>
; __device__ __forceinline__ void gemm_phase(LAS unsigned char* lds, const Gemm g, const Sched& S, const Epi& E) {
;     ...
;         for (int t = 0; t < nt; t += 2) {
;             const bool last = (t == nt - 2);
;             const char* a1 = cA + (size_t)(t + 1) * kstep;
;             const char* a2 = last ? nA : cA + (size_t)(t + 2) * kstep; const char* b2 = last ? nB : cB + (size_t)(t + 2) * kstep;
;             const char* a3 = a2 + kstep; const char* b3 = b2 + kstep;
;             if (last && has_next) S.a_ready(nxt);
;             if constexpr (SP2) {
;             PG8_LDB(B0, 0, 0); PG8_LDB(B1, 0, 1); PG8_SCHED; PG8_LDA(At, 0, 0); PG8_STAGE(PG8_SA(1, 1), a1 + hstep, voffA);
;             PG8_WAIT_V(8); PG8_WAIT_L(0); PG8_BAR; PG8_MMA(0, 0, At, B0); PG8_MMA(0, 1, At, B1); PG8_BAR; PG8_SCHED;
;             PG8_LDA(At, 0, 1); PG8_STAGE(PG8_SB(0, 0), b2, voffB); PG8_STAGE(PG8_SB(0, 1), b2 + hstep, voffB); PG8_STAGE(PG8_SA(0, 0), a2, voffA);
;             PG8_WAIT_V(8); PG8_WAIT_L(0); PG8_BAR; PG8_MMA(1, 0, At, B0); PG8_MMA(1, 1, At, B1); PG8_BAR; PG8_SCHED;
;             PG8_LDB(B0, 1, 0); PG8_LDB(B1, 1, 1); PG8_SCHED; PG8_LDA(At, 1, 0); PG8_STAGE(PG8_SA(0, 1), a2 + hstep, voffA);
;             PG8_WAIT_V(8); PG8_WAIT_L(0); PG8_BAR; PG8_MMA(0, 0, At, B0); PG8_MMA(0, 1, At, B1); PG8_BAR; PG8_SCHED;
;             PG8_LDA(At, 1, 1); PG8_STAGE(PG8_SB(1, 0), b3, voffB); PG8_STAGE(PG8_SB(1, 1), b3 + hstep, voffB); PG8_STAGE(PG8_SA(1, 0), a3, voffA);
;             PG8_WAIT_V(8); PG8_WAIT_L(0); PG8_BAR; PG8_MMA(1, 0, At, B0); PG8_MMA(1, 1, At, B1); PG8_BAR; PG8_SCHED;
.LBB0_257:
	s_add_u32 s24, s22, 0x100
	s_addc_u32 s25, s23, 0
	s_add_i32 s50, 0, 0x10000
	s_cmpk_eq_i32 s49, 0x54
	s_cselect_b32 s29, s1, s25
	s_cselect_b32 s28, s0, s24
	s_cselect_b32 s27, s21, s48
	s_cselect_b32 s26, s20, s47
	s_add_i32 s51, 0, 0x14000
	v_add_u32_e32 v126, s50, v247
	v_add_u32_e32 v158, s51, v247
	ds_read_b128 v[90:93], v126
	ds_read_b128 v[102:105], v126 offset:1024
	ds_read_b128 v[114:117], v126 offset:2048
	ds_read_b128 v[126:129], v126 offset:3072
	ds_read_b128 v[138:141], v158
	ds_read_b128 v[142:145], v158 offset:1024
	ds_read_b128 v[154:157], v158 offset:2048
	ds_read_b128 v[158:161], v158 offset:3072
	v_lshl_add_u64 v[186:187], s[22:23], 0, v[200:201]
	s_add_i32 m0, s6, 0xc000
	ds_read_b128 v[162:165], v249
	ds_read_b128 v[166:169], v249 offset:1024
	ds_read_b128 v[170:173], v249 offset:2048
	ds_read_b128 v[174:177], v249 offset:3072
	ds_read_b128 v[178:181], v249 offset:4096
	ds_read_b128 v[182:185], v249 offset:5120
	ds_read_b128 v[204:207], v249 offset:6144
	ds_read_b128 v[208:211], v249 offset:7168
	global_load_lds_dwordx4 v[186:187], off
	v_lshl_add_u64 v[186:187], s[22:23], 0, v[202:203]
	s_add_i32 m0, s6, 0xe000
	s_nop 0
	global_load_lds_dwordx4 v[186:187], off
	s_waitcnt vmcnt(8)
	s_waitcnt lgkmcnt(0)
	s_setprio 1
	s_barrier
	v_mfma_f32_16x16x32_bf16 v[150:153], v[90:93], v[162:165], v[150:153]
	v_mfma_f32_16x16x32_bf16 v[150:153], v[102:105], v[166:169], v[150:153]
	v_mfma_f32_16x16x32_bf16 v[146:149], v[114:117], v[162:165], v[146:149]
	v_mfma_f32_16x16x32_bf16 v[146:149], v[126:129], v[166:169], v[146:149]
	v_mfma_f32_16x16x32_bf16 v[118:121], v[114:117], v[170:173], v[118:121]
	v_mfma_f32_16x16x32_bf16 v[118:121], v[126:129], v[174:177], v[118:121]
	v_mfma_f32_16x16x32_bf16 v[122:125], v[90:93], v[170:173], v[122:125]
	v_mfma_f32_16x16x32_bf16 v[122:125], v[102:105], v[174:177], v[122:125]
	v_mfma_f32_16x16x32_bf16 v[98:101], v[90:93], v[178:181], v[98:101]
	v_mfma_f32_16x16x32_bf16 v[98:101], v[102:105], v[182:185], v[98:101]
	v_mfma_f32_16x16x32_bf16 v[94:97], v[114:117], v[178:181], v[94:97]
	v_mfma_f32_16x16x32_bf16 v[94:97], v[126:129], v[182:185], v[94:97]
	v_mfma_f32_16x16x32_bf16 v[74:77], v[114:117], v[204:207], v[74:77]
	v_mfma_f32_16x16x32_bf16 v[74:77], v[126:129], v[208:211], v[74:77]
	v_mfma_f32_16x16x32_bf16 v[78:81], v[90:93], v[204:207], v[78:81]
	v_mfma_f32_16x16x32_bf16 v[78:81], v[102:105], v[208:211], v[78:81]
	s_setprio 0
	s_setprio 1
	v_mfma_f32_16x16x32_bf16 v[134:137], v[138:141], v[162:165], v[134:137]
	v_mfma_f32_16x16x32_bf16 v[134:137], v[142:145], v[166:169], v[134:137]
	v_mfma_f32_16x16x32_bf16 v[130:133], v[154:157], v[162:165], v[130:133]
	v_mfma_f32_16x16x32_bf16 v[130:133], v[158:161], v[166:169], v[130:133]
	v_mfma_f32_16x16x32_bf16 v[106:109], v[154:157], v[170:173], v[106:109]
	v_mfma_f32_16x16x32_bf16 v[106:109], v[158:161], v[174:177], v[106:109]
	v_mfma_f32_16x16x32_bf16 v[110:113], v[138:141], v[170:173], v[110:113]
	v_mfma_f32_16x16x32_bf16 v[110:113], v[142:145], v[174:177], v[110:113]
	v_mfma_f32_16x16x32_bf16 v[86:89], v[138:141], v[178:181], v[86:89]
	v_mfma_f32_16x16x32_bf16 v[86:89], v[142:145], v[182:185], v[86:89]
	v_mfma_f32_16x16x32_bf16 v[82:85], v[154:157], v[178:181], v[82:85]
	v_mfma_f32_16x16x32_bf16 v[82:85], v[158:161], v[182:185], v[82:85]
	v_mfma_f32_16x16x32_bf16 v[66:69], v[154:157], v[204:207], v[66:69]
	v_mfma_f32_16x16x32_bf16 v[66:69], v[158:161], v[208:211], v[66:69]
	v_mfma_f32_16x16x32_bf16 v[70:73], v[138:141], v[204:207], v[70:73]
	v_mfma_f32_16x16x32_bf16 v[70:73], v[142:145], v[208:211], v[70:73]
	s_setprio 0
	s_barrier
	s_add_i32 s22, s50, s2
	v_lshl_add_u64 v[186:187], s[26:27], 0, v[0:1]
	s_mov_b32 m0, s22
	ds_read_b128 v[162:165], v249 offset:16384
	ds_read_b128 v[166:169], v249 offset:17408
	ds_read_b128 v[170:173], v249 offset:18432
	ds_read_b128 v[174:177], v249 offset:19456
	ds_read_b128 v[178:181], v249 offset:20480
	ds_read_b128 v[182:185], v249 offset:21504
	ds_read_b128 v[204:207], v249 offset:22528
	ds_read_b128 v[208:211], v249 offset:23552
	global_load_lds_dwordx4 v[186:187], off
	s_add_i32 m0, s22, 0x2000
	s_add_u32 s22, s26, 0x160000
	v_lshl_add_u64 v[188:189], s[26:27], 0, v[194:195]
	s_addc_u32 s23, s27, 0
	s_add_i32 s50, s51, s2
	global_load_lds_dwordx4 v[188:189], off
	v_lshl_add_u64 v[190:191], s[22:23], 0, v[0:1]
	s_mov_b32 m0, s50
	v_lshl_add_u64 v[192:193], s[28:29], 0, v[196:197]
	global_load_lds_dwordx4 v[190:191], off
	v_lshl_add_u64 v[190:191], s[22:23], 0, v[194:195]
	s_add_i32 m0, s50, 0x2000
	s_nop 0
	global_load_lds_dwordx4 v[190:191], off
	v_lshl_add_u64 v[190:191], s[28:29], 0, v[198:199]
	s_mov_b32 m0, s6
	s_nop 0
	global_load_lds_dwordx4 v[190:191], off
	s_mov_b32 m0, s7
	s_nop 0
	global_load_lds_dwordx4 v[192:193], off
	s_waitcnt vmcnt(8)
	s_waitcnt lgkmcnt(0)
	s_setprio 1
	s_barrier
; #define PG8_STAGE(bufoff, gbase, voff) do { _Pragma("unroll") for (int _i = 0; _i < 2; ++_i) \
;         __builtin_amdgcn_global_load_lds((const unsigned*)((const char*)(gbase) + (voff)[_i]), (LAS unsigned*)(lds + (bufoff) + ldsw + _i * 8192), 16, 0, 0); } while (0)
; #define PG8_LDA(dst, b, h) do { _Pragma("unroll") for (int m = 0; m < 4; ++m) _Pragma("unroll") for (int k = 0; k < 2; ++k) dst[m][k] = *(const LAS bf16x8*)(lds + PG8_SA(b, h) + aoff + m * 2048 + k * 1024); } while (0)
; #define PG8_LDB(dst, b, h) do { _Pragma("unroll") for (int n = 0; n < 2; ++n) _Pragma("unroll") for (int k = 0; k < 2; ++k) dst[n][k] = *(const LAS bf16x8*)(lds + PG8_SB(b, h) + boff + n * 2048 + k * 1024); } while (0)
; template <class Epi, class Sched, bool ALIGN_EPI = false, bool SP2 = false>
; __device__ __forceinline__ void gemm_phase(LAS unsigned char* lds, const Gemm g, const Sched& S, const Epi& E) {
;     ...
;         for (int t = 0; t < nt; t += 2) {
;             const bool last = (t == nt - 2);
;             const char* a1 = cA + (size_t)(t + 1) * kstep;
;             const char* a2 = last ? nA : cA + (size_t)(t + 2) * kstep; const char* b2 = last ? nB : cB + (size_t)(t + 2) * kstep;
;             const char* a3 = a2 + kstep; const char* b3 = b2 + kstep;
;             if (last && has_next) S.a_ready(nxt);
;             if constexpr (SP2) {
;             PG8_LDB(B0, 0, 0); PG8_LDB(B1, 0, 1); PG8_SCHED; PG8_LDA(At, 0, 0); PG8_STAGE(PG8_SA(1, 1), a1 + hstep, voffA);
;             PG8_WAIT_V(8); PG8_WAIT_L(0); PG8_BAR; PG8_MMA(0, 0, At, B0); PG8_MMA(0, 1, At, B1); PG8_BAR; PG8_SCHED;
;             PG8_LDA(At, 0, 1); PG8_STAGE(PG8_SB(0, 0), b2, voffB); PG8_STAGE(PG8_SB(0, 1), b2 + hstep, voffB); PG8_STAGE(PG8_SA(0, 0), a2, voffA);
;             PG8_WAIT_V(8); PG8_WAIT_L(0); PG8_BAR; PG8_MMA(1, 0, At, B0); PG8_MMA(1, 1, At, B1); PG8_BAR; PG8_SCHED;
;             PG8_LDB(B0, 1, 0); PG8_LDB(B1, 1, 1); PG8_SCHED; PG8_LDA(At, 1, 0); PG8_STAGE(PG8_SA(0, 1), a2 + hstep, voffA);
;             PG8_WAIT_V(8); PG8_WAIT_L(0); PG8_BAR; PG8_MMA(0, 0, At, B0); PG8_MMA(0, 1, At, B1); PG8_BAR; PG8_SCHED;
;             PG8_LDA(At, 1, 1); PG8_STAGE(PG8_SB(1, 0), b3, voffB); PG8_STAGE(PG8_SB(1, 1), b3 + hstep, voffB); PG8_STAGE(PG8_SA(1, 0), a3, voffA);
;             PG8_WAIT_V(8); PG8_WAIT_L(0); PG8_BAR; PG8_MMA(1, 0, At, B0); PG8_MMA(1, 1, At, B1); PG8_BAR; PG8_SCHED;
	v_mfma_f32_16x16x32_bf16 v[62:65], v[90:93], v[162:165], v[62:65]
	v_mfma_f32_16x16x32_bf16 v[62:65], v[102:105], v[166:169], v[62:65]
	v_mfma_f32_16x16x32_bf16 v[58:61], v[114:117], v[162:165], v[58:61]
	v_mfma_f32_16x16x32_bf16 v[58:61], v[126:129], v[166:169], v[58:61]
	v_mfma_f32_16x16x32_bf16 v[42:45], v[114:117], v[170:173], v[42:45]
	v_mfma_f32_16x16x32_bf16 v[42:45], v[126:129], v[174:177], v[42:45]
	v_mfma_f32_16x16x32_bf16 v[46:49], v[90:93], v[170:173], v[46:49]
	v_mfma_f32_16x16x32_bf16 v[46:49], v[102:105], v[174:177], v[46:49]
	v_mfma_f32_16x16x32_bf16 v[30:33], v[90:93], v[178:181], v[30:33]
	v_mfma_f32_16x16x32_bf16 v[30:33], v[102:105], v[182:185], v[30:33]
	v_mfma_f32_16x16x32_bf16 v[26:29], v[114:117], v[178:181], v[26:29]
	v_mfma_f32_16x16x32_bf16 v[26:29], v[126:129], v[182:185], v[26:29]
	v_mfma_f32_16x16x32_bf16 v[10:13], v[114:117], v[204:207], v[10:13]
	v_mfma_f32_16x16x32_bf16 v[10:13], v[126:129], v[208:211], v[10:13]
	v_mfma_f32_16x16x32_bf16 v[14:17], v[90:93], v[204:207], v[14:17]
	v_mfma_f32_16x16x32_bf16 v[14:17], v[102:105], v[208:211], v[14:17]
	s_setprio 0
	s_setprio 1
	v_mfma_f32_16x16x32_bf16 v[54:57], v[138:141], v[162:165], v[54:57]
	v_mfma_f32_16x16x32_bf16 v[54:57], v[142:145], v[166:169], v[54:57]
	v_mfma_f32_16x16x32_bf16 v[50:53], v[154:157], v[162:165], v[50:53]
	v_mfma_f32_16x16x32_bf16 v[50:53], v[158:161], v[166:169], v[50:53]
	v_mfma_f32_16x16x32_bf16 v[34:37], v[154:157], v[170:173], v[34:37]
	v_mfma_f32_16x16x32_bf16 v[34:37], v[158:161], v[174:177], v[34:37]
	v_mfma_f32_16x16x32_bf16 v[38:41], v[138:141], v[170:173], v[38:41]
	v_mfma_f32_16x16x32_bf16 v[38:41], v[142:145], v[174:177], v[38:41]
	v_mfma_f32_16x16x32_bf16 v[22:25], v[138:141], v[178:181], v[22:25]
	v_mfma_f32_16x16x32_bf16 v[22:25], v[142:145], v[182:185], v[22:25]
	v_mfma_f32_16x16x32_bf16 v[18:21], v[154:157], v[178:181], v[18:21]
	v_mfma_f32_16x16x32_bf16 v[18:21], v[158:161], v[182:185], v[18:21]
	v_mfma_f32_16x16x32_bf16 v[2:5], v[154:157], v[204:207], v[2:5]
	v_mfma_f32_16x16x32_bf16 v[2:5], v[158:161], v[208:211], v[2:5]
	v_mfma_f32_16x16x32_bf16 v[6:9], v[138:141], v[204:207], v[6:9]
	v_mfma_f32_16x16x32_bf16 v[6:9], v[142:145], v[208:211], v[6:9]
	s_setprio 0
	s_barrier
	s_add_i32 s50, 0, 0x18000
	s_add_i32 s51, 0, 0x1c000
	v_add_u32_e32 v126, s50, v247
	v_add_u32_e32 v158, s51, v247
	ds_read_b128 v[90:93], v126
	ds_read_b128 v[102:105], v126 offset:1024
	ds_read_b128 v[114:117], v126 offset:2048
	ds_read_b128 v[126:129], v126 offset:3072
	ds_read_b128 v[138:141], v158
	ds_read_b128 v[142:145], v158 offset:1024
	ds_read_b128 v[154:157], v158 offset:2048
	ds_read_b128 v[158:161], v158 offset:3072
	s_add_u32 s22, s28, 0x160000
	s_addc_u32 s23, s29, 0
	s_mov_b32 m0, s8
	v_lshl_add_u64 v[212:213], s[22:23], 0, v[198:199]
	ds_read_b128 v[162:165], v249 offset:32768
	ds_read_b128 v[166:169], v249 offset:33792
	ds_read_b128 v[170:173], v249 offset:34816
	ds_read_b128 v[174:177], v249 offset:35840
	ds_read_b128 v[178:181], v249 offset:36864
	ds_read_b128 v[182:185], v249 offset:37888
	ds_read_b128 v[204:207], v249 offset:38912
	ds_read_b128 v[208:211], v249 offset:39936
	global_load_lds_dwordx4 v[212:213], off
	v_lshl_add_u64 v[212:213], s[22:23], 0, v[196:197]
	s_mov_b32 m0, s31
	s_nop 0
	global_load_lds_dwordx4 v[212:213], off
	s_waitcnt vmcnt(8)
	s_waitcnt lgkmcnt(0)
	s_setprio 1
	s_barrier
	v_mfma_f32_16x16x32_bf16 v[150:153], v[90:93], v[162:165], v[150:153]
	v_mfma_f32_16x16x32_bf16 v[150:153], v[102:105], v[166:169], v[150:153]
	v_mfma_f32_16x16x32_bf16 v[146:149], v[114:117], v[162:165], v[146:149]
	v_mfma_f32_16x16x32_bf16 v[146:149], v[126:129], v[166:169], v[146:149]
	v_mfma_f32_16x16x32_bf16 v[118:121], v[114:117], v[170:173], v[118:121]
	v_mfma_f32_16x16x32_bf16 v[118:121], v[126:129], v[174:177], v[118:121]
	v_mfma_f32_16x16x32_bf16 v[122:125], v[90:93], v[170:173], v[122:125]
	v_mfma_f32_16x16x32_bf16 v[122:125], v[102:105], v[174:177], v[122:125]
	v_mfma_f32_16x16x32_bf16 v[98:101], v[90:93], v[178:181], v[98:101]
	v_mfma_f32_16x16x32_bf16 v[98:101], v[102:105], v[182:185], v[98:101]
	v_mfma_f32_16x16x32_bf16 v[94:97], v[114:117], v[178:181], v[94:97]
	v_mfma_f32_16x16x32_bf16 v[94:97], v[126:129], v[182:185], v[94:97]
	v_mfma_f32_16x16x32_bf16 v[74:77], v[114:117], v[204:207], v[74:77]
	v_mfma_f32_16x16x32_bf16 v[74:77], v[126:129], v[208:211], v[74:77]
	v_mfma_f32_16x16x32_bf16 v[78:81], v[90:93], v[204:207], v[78:81]
	v_mfma_f32_16x16x32_bf16 v[78:81], v[102:105], v[208:211], v[78:81]
	s_setprio 0
	s_setprio 1
	v_mfma_f32_16x16x32_bf16 v[134:137], v[138:141], v[162:165], v[134:137]
	v_mfma_f32_16x16x32_bf16 v[134:137], v[142:145], v[166:169], v[134:137]
	v_mfma_f32_16x16x32_bf16 v[130:133], v[154:157], v[162:165], v[130:133]
	v_mfma_f32_16x16x32_bf16 v[130:133], v[158:161], v[166:169], v[130:133]
	v_mfma_f32_16x16x32_bf16 v[106:109], v[154:157], v[170:173], v[106:109]
	v_mfma_f32_16x16x32_bf16 v[106:109], v[158:161], v[174:177], v[106:109]
	v_mfma_f32_16x16x32_bf16 v[110:113], v[138:141], v[170:173], v[110:113]
	v_mfma_f32_16x16x32_bf16 v[110:113], v[142:145], v[174:177], v[110:113]
	v_mfma_f32_16x16x32_bf16 v[86:89], v[138:141], v[178:181], v[86:89]
	v_mfma_f32_16x16x32_bf16 v[86:89], v[142:145], v[182:185], v[86:89]
	v_mfma_f32_16x16x32_bf16 v[82:85], v[154:157], v[178:181], v[82:85]
	v_mfma_f32_16x16x32_bf16 v[82:85], v[158:161], v[182:185], v[82:85]
	v_mfma_f32_16x16x32_bf16 v[66:69], v[154:157], v[204:207], v[66:69]
	v_mfma_f32_16x16x32_bf16 v[66:69], v[158:161], v[208:211], v[66:69]
	v_mfma_f32_16x16x32_bf16 v[70:73], v[138:141], v[204:207], v[70:73]
	v_mfma_f32_16x16x32_bf16 v[70:73], v[142:145], v[208:211], v[70:73]
	s_setprio 0
	s_barrier
; #define PG8_STAGE(bufoff, gbase, voff) do { _Pragma("unroll") for (int _i = 0; _i < 2; ++_i) \
;         __builtin_amdgcn_global_load_lds((const unsigned*)((const char*)(gbase) + (voff)[_i]), (LAS unsigned*)(lds + (bufoff) + ldsw + _i * 8192), 16, 0, 0); } while (0)
; #define PG8_LDA(dst, b, h) do { _Pragma("unroll") for (int m = 0; m < 4; ++m) _Pragma("unroll") for (int k = 0; k < 2; ++k) dst[m][k] = *(const LAS bf16x8*)(lds + PG8_SA(b, h) + aoff + m * 2048 + k * 1024); } while (0)
; #define PG8_LDB(dst, b, h) do { _Pragma("unroll") for (int n = 0; n < 2; ++n) _Pragma("unroll") for (int k = 0; k < 2; ++k) dst[n][k] = *(const LAS bf16x8*)(lds + PG8_SB(b, h) + boff + n * 2048 + k * 1024); } while (0)
; template <class Epi, class Sched, bool ALIGN_EPI = false, bool SP2 = false>
; __device__ __forceinline__ void gemm_phase(LAS unsigned char* lds, const Gemm g, const Sched& S, const Epi& E) {
;     ...
;         for (int t = 0; t < nt; t += 2) {
;             const bool last = (t == nt - 2);
;             const char* a1 = cA + (size_t)(t + 1) * kstep;
;             const char* a2 = last ? nA : cA + (size_t)(t + 2) * kstep; const char* b2 = last ? nB : cB + (size_t)(t + 2) * kstep;
;             const char* a3 = a2 + kstep; const char* b3 = b2 + kstep;
;             if (last && has_next) S.a_ready(nxt);
;             if constexpr (SP2) {
;             PG8_LDB(B0, 0, 0); PG8_LDB(B1, 0, 1); PG8_SCHED; PG8_LDA(At, 0, 0); PG8_STAGE(PG8_SA(1, 1), a1 + hstep, voffA);
;             PG8_WAIT_V(8); PG8_WAIT_L(0); PG8_BAR; PG8_MMA(0, 0, At, B0); PG8_MMA(0, 1, At, B1); PG8_BAR; PG8_SCHED;
;             PG8_LDA(At, 0, 1); PG8_STAGE(PG8_SB(0, 0), b2, voffB); PG8_STAGE(PG8_SB(0, 1), b2 + hstep, voffB); PG8_STAGE(PG8_SA(0, 0), a2, voffA);
;             PG8_WAIT_V(8); PG8_WAIT_L(0); PG8_BAR; PG8_MMA(1, 0, At, B0); PG8_MMA(1, 1, At, B1); PG8_BAR; PG8_SCHED;
;             PG8_LDB(B0, 1, 0); PG8_LDB(B1, 1, 1); PG8_SCHED; PG8_LDA(At, 1, 0); PG8_STAGE(PG8_SA(0, 1), a2 + hstep, voffA);
;             PG8_WAIT_V(8); PG8_WAIT_L(0); PG8_BAR; PG8_MMA(0, 0, At, B0); PG8_MMA(0, 1, At, B1); PG8_BAR; PG8_SCHED;
;             PG8_LDA(At, 1, 1); PG8_STAGE(PG8_SB(1, 0), b3, voffB); PG8_STAGE(PG8_SB(1, 1), b3 + hstep, voffB); PG8_STAGE(PG8_SA(1, 0), a3, voffA);
;             PG8_WAIT_V(8); PG8_WAIT_L(0); PG8_BAR; PG8_MMA(1, 0, At, B0); PG8_MMA(1, 1, At, B1); PG8_BAR; PG8_SCHED;
	s_add_i32 s22, s50, s2
	v_lshl_add_u64 v[186:187], v[186:187], 0, s[12:13]
	s_mov_b32 m0, s22
	ds_read_b128 v[162:165], v249 offset:49152
	ds_read_b128 v[166:169], v249 offset:50176
	ds_read_b128 v[170:173], v249 offset:51200
	ds_read_b128 v[174:177], v249 offset:52224
	ds_read_b128 v[178:181], v249 offset:53248
	ds_read_b128 v[182:185], v249 offset:54272
	ds_read_b128 v[204:207], v249 offset:55296
	ds_read_b128 v[208:211], v249 offset:56320
	global_load_lds_dwordx4 v[186:187], off
	s_add_i32 m0, s22, 0x2000
	s_add_u32 s22, s26, 0x160080
	v_lshl_add_u64 v[186:187], v[188:189], 0, s[12:13]
	s_addc_u32 s23, s27, 0
	s_add_i32 s26, s51, s2
	global_load_lds_dwordx4 v[186:187], off
	v_lshl_add_u64 v[186:187], s[22:23], 0, v[0:1]
	s_mov_b32 m0, s26
	s_nop 0
	global_load_lds_dwordx4 v[186:187], off
	v_lshl_add_u64 v[186:187], s[22:23], 0, v[194:195]
	s_add_i32 m0, s26, 0x2000
	s_nop 0
	global_load_lds_dwordx4 v[186:187], off
	v_lshl_add_u64 v[186:187], v[190:191], 0, s[12:13]
	s_mov_b32 m0, s35
	s_nop 0
	global_load_lds_dwordx4 v[186:187], off
	v_lshl_add_u64 v[186:187], v[192:193], 0, s[12:13]
	s_mov_b32 m0, s40
	s_nop 0
	global_load_lds_dwordx4 v[186:187], off
	s_waitcnt vmcnt(8)
	s_waitcnt lgkmcnt(0)
	s_setprio 1
	s_barrier
	v_mfma_f32_16x16x32_bf16 v[62:65], v[90:93], v[162:165], v[62:65]
	v_mfma_f32_16x16x32_bf16 v[62:65], v[102:105], v[166:169], v[62:65]
	v_mfma_f32_16x16x32_bf16 v[58:61], v[114:117], v[162:165], v[58:61]
	v_mfma_f32_16x16x32_bf16 v[58:61], v[126:129], v[166:169], v[58:61]
	v_mfma_f32_16x16x32_bf16 v[42:45], v[114:117], v[170:173], v[42:45]
	v_mfma_f32_16x16x32_bf16 v[42:45], v[126:129], v[174:177], v[42:45]
	v_mfma_f32_16x16x32_bf16 v[46:49], v[90:93], v[170:173], v[46:49]
	v_mfma_f32_16x16x32_bf16 v[46:49], v[102:105], v[174:177], v[46:49]
	v_mfma_f32_16x16x32_bf16 v[30:33], v[90:93], v[178:181], v[30:33]
	v_mfma_f32_16x16x32_bf16 v[30:33], v[102:105], v[182:185], v[30:33]
	v_mfma_f32_16x16x32_bf16 v[26:29], v[114:117], v[178:181], v[26:29]
	v_mfma_f32_16x16x32_bf16 v[26:29], v[126:129], v[182:185], v[26:29]
	v_mfma_f32_16x16x32_bf16 v[10:13], v[114:117], v[204:207], v[10:13]
	v_mfma_f32_16x16x32_bf16 v[10:13], v[126:129], v[208:211], v[10:13]
	v_mfma_f32_16x16x32_bf16 v[14:17], v[90:93], v[204:207], v[14:17]
	v_mfma_f32_16x16x32_bf16 v[14:17], v[102:105], v[208:211], v[14:17]
	s_setprio 0
	s_setprio 1
	v_mfma_f32_16x16x32_bf16 v[54:57], v[138:141], v[162:165], v[54:57]
	v_mfma_f32_16x16x32_bf16 v[54:57], v[142:145], v[166:169], v[54:57]
	v_mfma_f32_16x16x32_bf16 v[50:53], v[154:157], v[162:165], v[50:53]
	v_mfma_f32_16x16x32_bf16 v[50:53], v[158:161], v[166:169], v[50:53]
	v_mfma_f32_16x16x32_bf16 v[34:37], v[154:157], v[170:173], v[34:37]
	v_mfma_f32_16x16x32_bf16 v[34:37], v[158:161], v[174:177], v[34:37]
	v_mfma_f32_16x16x32_bf16 v[38:41], v[138:141], v[170:173], v[38:41]
	v_mfma_f32_16x16x32_bf16 v[38:41], v[142:145], v[174:177], v[38:41]
	v_mfma_f32_16x16x32_bf16 v[22:25], v[138:141], v[178:181], v[22:25]
	v_mfma_f32_16x16x32_bf16 v[22:25], v[142:145], v[182:185], v[22:25]
	v_mfma_f32_16x16x32_bf16 v[18:21], v[154:157], v[178:181], v[18:21]
	v_mfma_f32_16x16x32_bf16 v[18:21], v[158:161], v[182:185], v[18:21]
	v_mfma_f32_16x16x32_bf16 v[2:5], v[154:157], v[204:207], v[2:5]
	v_mfma_f32_16x16x32_bf16 v[2:5], v[158:161], v[208:211], v[2:5]
	v_mfma_f32_16x16x32_bf16 v[6:9], v[138:141], v[204:207], v[6:9]
	v_mfma_f32_16x16x32_bf16 v[6:9], v[142:145], v[208:211], v[6:9]
	s_setprio 0
	s_barrier
	s_add_i32 s49, s49, 2
	s_add_u32 s47, s47, 0x100
	s_addc_u32 s48, s48, 0
	s_cmpk_gt_u32 s49, 0x55
	s_mov_b64 s[22:23], s[24:25]
	s_cbranch_scc0 .LBB0_257
	s_and_b64 vcc, exec, s[18:19]
	s_cbranch_vccz .LBB0_260
	s_barrier

; #define PG8_STAGE(bufoff, gbase, voff) do { _Pragma("unroll") for (int _i = 0; _i < 2; ++_i) \
;         __builtin_amdgcn_global_load_lds((const unsigned*)((const char*)(gbase) + (voff)[_i]), (LAS unsigned*)(lds + (bufoff) + ldsw + _i * 8192), 16, 0, 0); } while (0)
; #define PG8_LDA(dst, b, h) do { _Pragma("unroll") for (int m = 0; m < 4; ++m) _Pragma("unroll") for (int k = 0; k < 2; ++k) dst[m][k] = *(const LAS bf16x8*)(lds + PG8_SA(b, h) + aoff + m * 2048 + k * 1024); } while (0)
; #define PG8_LDB(dst, b, h) do { _Pragma("unroll") for (int n = 0; n < 2; ++n) _Pragma("unroll") for (int k = 0; k < 2; ++k) dst[n][k] = *(const LAS bf16x8*)(lds + PG8_SB(b, h) + boff + n * 2048 + k * 1024); } while (0)
; template <class Epi, class Sched, bool ALIGN_EPI = false, bool SP2 = false>
; __device__ __forceinline__ void gemm_phase(LAS unsigned char* lds, const Gemm g, const Sched& S, const Epi& E) {
;     ...
;         for (int t = 0; t < nt; t += 2) {
;             const bool last = (t == nt - 2);
;             const char* a1 = cA + (size_t)(t + 1) * kstep;
;             const char* a2 = last ? nA : cA + (size_t)(t + 2) * kstep; const char* b2 = last ? nB : cB + (size_t)(t + 2) * kstep;
;             const char* a3 = a2 + kstep; const char* b3 = b2 + kstep;
;             if (last && has_next) S.a_ready(nxt);
;             if constexpr (SP2) {
;             PG8_LDB(B0, 0, 0); PG8_LDB(B1, 0, 1); PG8_SCHED; PG8_LDA(At, 0, 0); PG8_STAGE(PG8_SA(1, 1), a1 + hstep, voffA);
;             PG8_WAIT_V(8); PG8_WAIT_L(0); PG8_BAR; PG8_MMA(0, 0, At, B0); PG8_MMA(0, 1, At, B1); PG8_BAR; PG8_SCHED;
;             PG8_LDA(At, 0, 1); PG8_STAGE(PG8_SB(0, 0), b2, voffB); PG8_STAGE(PG8_SB(0, 1), b2 + hstep, voffB); PG8_STAGE(PG8_SA(0, 0), a2, voffA);
;             PG8_WAIT_V(8); PG8_WAIT_L(0); PG8_BAR; PG8_MMA(1, 0, At, B0); PG8_MMA(1, 1, At, B1); PG8_BAR; PG8_SCHED;
;             PG8_LDB(B0, 1, 0); PG8_LDB(B1, 1, 1); PG8_SCHED; PG8_LDA(At, 1, 0); PG8_STAGE(PG8_SA(0, 1), a2 + hstep, voffA);
;             PG8_WAIT_V(8); PG8_WAIT_L(0); PG8_BAR; PG8_MMA(0, 0, At, B0); PG8_MMA(0, 1, At, B1); PG8_BAR; PG8_SCHED;
;             PG8_LDA(At, 1, 1); PG8_STAGE(PG8_SB(1, 0), b3, voffB); PG8_STAGE(PG8_SB(1, 1), b3 + hstep, voffB); PG8_STAGE(PG8_SA(1, 0), a3, voffA);
;             PG8_WAIT_V(8); PG8_WAIT_L(0); PG8_BAR; PG8_MMA(1, 0, At, B0); PG8_MMA(1, 1, At, B1); PG8_BAR; PG8_SCHED;
.LBB0_359:
	s_add_u32 s28, s26, 0xfff80080
	s_addc_u32 s29, s27, -1
	s_add_i32 s41, 0, 0x10000
	s_cmp_eq_u32 s40, 28
	s_cselect_b32 s31, s6, s29
	s_cselect_b32 s30, s7, s28
	v_add_u32_e32 v0, s41, v159
	s_cselect_b32 s29, s8, s35
	s_cselect_b32 s28, s19, s21
	s_add_i32 s57, 0, 0x14000
	ds_read_b128 v[142:145], v0
	ds_read_b128 v[146:149], v0 offset:1024
	ds_read_b128 v[150:153], v0 offset:2048
	ds_read_b128 v[154:157], v0 offset:3072
	v_add_u32_e32 v0, s57, v159
	ds_read_b128 v[162:165], v0
	ds_read_b128 v[166:169], v0 offset:1024
	ds_read_b128 v[170:173], v0 offset:2048
	ds_read_b128 v[174:177], v0 offset:3072
	v_lshl_add_u64 v[210:211], s[26:27], 0, v[138:139]
	s_add_i32 m0, s44, 0xc000
	ds_read_b128 v[178:181], v161
	ds_read_b128 v[182:185], v161 offset:1024
	ds_read_b128 v[186:189], v161 offset:2048
	ds_read_b128 v[190:193], v161 offset:3072
	ds_read_b128 v[194:197], v161 offset:4096
	ds_read_b128 v[198:201], v161 offset:5120
	ds_read_b128 v[202:205], v161 offset:6144
	ds_read_b128 v[206:209], v161 offset:7168
	global_load_lds_dwordx4 v[210:211], off
	v_lshl_add_u64 v[210:211], s[26:27], 0, v[140:141]
	s_add_i32 m0, s44, 0xe000
	s_nop 0
	global_load_lds_dwordx4 v[210:211], off
	s_waitcnt vmcnt(8)
	s_waitcnt lgkmcnt(0)
	s_setprio 1
	s_barrier
	v_mfma_f32_16x16x32_bf16 v[126:129], v[142:145], v[178:181], v[126:129]
	v_mfma_f32_16x16x32_bf16 v[126:129], v[146:149], v[182:185], v[126:129]
	v_mfma_f32_16x16x32_bf16 v[122:125], v[150:153], v[178:181], v[122:125]
	v_mfma_f32_16x16x32_bf16 v[122:125], v[154:157], v[182:185], v[122:125]
	v_mfma_f32_16x16x32_bf16 v[106:109], v[150:153], v[186:189], v[106:109]
	v_mfma_f32_16x16x32_bf16 v[106:109], v[154:157], v[190:193], v[106:109]
	v_mfma_f32_16x16x32_bf16 v[110:113], v[142:145], v[186:189], v[110:113]
	v_mfma_f32_16x16x32_bf16 v[110:113], v[146:149], v[190:193], v[110:113]
	v_mfma_f32_16x16x32_bf16 v[94:97], v[142:145], v[194:197], v[94:97]
	v_mfma_f32_16x16x32_bf16 v[94:97], v[146:149], v[198:201], v[94:97]
	v_mfma_f32_16x16x32_bf16 v[90:93], v[150:153], v[194:197], v[90:93]
	v_mfma_f32_16x16x32_bf16 v[90:93], v[154:157], v[198:201], v[90:93]
	v_mfma_f32_16x16x32_bf16 v[74:77], v[150:153], v[202:205], v[74:77]
	v_mfma_f32_16x16x32_bf16 v[74:77], v[154:157], v[206:209], v[74:77]
	v_mfma_f32_16x16x32_bf16 v[78:81], v[142:145], v[202:205], v[78:81]
	v_mfma_f32_16x16x32_bf16 v[78:81], v[146:149], v[206:209], v[78:81]
	s_setprio 0
	s_setprio 1
	v_mfma_f32_16x16x32_bf16 v[118:121], v[162:165], v[178:181], v[118:121]
	v_mfma_f32_16x16x32_bf16 v[118:121], v[166:169], v[182:185], v[118:121]
	v_mfma_f32_16x16x32_bf16 v[114:117], v[170:173], v[178:181], v[114:117]
	v_mfma_f32_16x16x32_bf16 v[114:117], v[174:177], v[182:185], v[114:117]
	v_mfma_f32_16x16x32_bf16 v[98:101], v[170:173], v[186:189], v[98:101]
	v_mfma_f32_16x16x32_bf16 v[98:101], v[174:177], v[190:193], v[98:101]
	v_mfma_f32_16x16x32_bf16 v[102:105], v[162:165], v[186:189], v[102:105]
	v_mfma_f32_16x16x32_bf16 v[102:105], v[166:169], v[190:193], v[102:105]
	v_mfma_f32_16x16x32_bf16 v[86:89], v[162:165], v[194:197], v[86:89]
	v_mfma_f32_16x16x32_bf16 v[86:89], v[166:169], v[198:201], v[86:89]
	v_mfma_f32_16x16x32_bf16 v[82:85], v[170:173], v[194:197], v[82:85]
	v_mfma_f32_16x16x32_bf16 v[82:85], v[174:177], v[198:201], v[82:85]
	v_mfma_f32_16x16x32_bf16 v[66:69], v[170:173], v[202:205], v[66:69]
	v_mfma_f32_16x16x32_bf16 v[66:69], v[174:177], v[206:209], v[66:69]
	v_mfma_f32_16x16x32_bf16 v[70:73], v[162:165], v[202:205], v[70:73]
	v_mfma_f32_16x16x32_bf16 v[70:73], v[166:169], v[206:209], v[70:73]
	s_setprio 0
	s_barrier
	s_add_i32 s41, s41, s9
	v_lshl_add_u64 v[210:211], s[28:29], 0, v[134:135]
	s_mov_b32 m0, s41
	ds_read_b128 v[178:181], v161 offset:16384
	ds_read_b128 v[182:185], v161 offset:17408
	ds_read_b128 v[186:189], v161 offset:18432
	ds_read_b128 v[190:193], v161 offset:19456
	ds_read_b128 v[194:197], v161 offset:20480
	ds_read_b128 v[198:201], v161 offset:21504
	ds_read_b128 v[202:205], v161 offset:22528
	ds_read_b128 v[206:209], v161 offset:23552
	global_load_lds_dwordx4 v[210:211], off
	s_add_i32 m0, s41, 0x2000
	s_add_u32 s58, s28, 0x80000
	v_lshl_add_u64 v[212:213], s[28:29], 0, v[130:131]
	s_addc_u32 s59, s29, 0
	s_add_i32 s41, s57, s9
	global_load_lds_dwordx4 v[212:213], off
	v_lshl_add_u64 v[214:215], s[58:59], 0, v[134:135]
	s_mov_b32 m0, s41
	v_lshl_add_u64 v[216:217], s[30:31], 0, v[132:133]
	global_load_lds_dwordx4 v[214:215], off
	v_lshl_add_u64 v[214:215], s[58:59], 0, v[130:131]
	s_add_i32 m0, s41, 0x2000
	s_nop 0
	global_load_lds_dwordx4 v[214:215], off
	v_lshl_add_u64 v[214:215], s[30:31], 0, v[136:137]
	s_mov_b32 m0, s44
	s_nop 0
	global_load_lds_dwordx4 v[214:215], off
	s_mov_b32 m0, s45
	s_nop 0
	global_load_lds_dwordx4 v[216:217], off
	s_waitcnt vmcnt(8)
	s_waitcnt lgkmcnt(0)
	s_setprio 1
	s_barrier
; #define PG8_STAGE(bufoff, gbase, voff) do { _Pragma("unroll") for (int _i = 0; _i < 2; ++_i) \
;         __builtin_amdgcn_global_load_lds((const unsigned*)((const char*)(gbase) + (voff)[_i]), (LAS unsigned*)(lds + (bufoff) + ldsw + _i * 8192), 16, 0, 0); } while (0)
; #define PG8_LDA(dst, b, h) do { _Pragma("unroll") for (int m = 0; m < 4; ++m) _Pragma("unroll") for (int k = 0; k < 2; ++k) dst[m][k] = *(const LAS bf16x8*)(lds + PG8_SA(b, h) + aoff + m * 2048 + k * 1024); } while (0)
; #define PG8_LDB(dst, b, h) do { _Pragma("unroll") for (int n = 0; n < 2; ++n) _Pragma("unroll") for (int k = 0; k < 2; ++k) dst[n][k] = *(const LAS bf16x8*)(lds + PG8_SB(b, h) + boff + n * 2048 + k * 1024); } while (0)
; template <class Epi, class Sched, bool ALIGN_EPI = false, bool SP2 = false>
; __device__ __forceinline__ void gemm_phase(LAS unsigned char* lds, const Gemm g, const Sched& S, const Epi& E) {
;     ...
;         for (int t = 0; t < nt; t += 2) {
;             const bool last = (t == nt - 2);
;             const char* a1 = cA + (size_t)(t + 1) * kstep;
;             const char* a2 = last ? nA : cA + (size_t)(t + 2) * kstep; const char* b2 = last ? nB : cB + (size_t)(t + 2) * kstep;
;             const char* a3 = a2 + kstep; const char* b3 = b2 + kstep;
;             if (last && has_next) S.a_ready(nxt);
;             if constexpr (SP2) {
;             PG8_LDB(B0, 0, 0); PG8_LDB(B1, 0, 1); PG8_SCHED; PG8_LDA(At, 0, 0); PG8_STAGE(PG8_SA(1, 1), a1 + hstep, voffA);
;             PG8_WAIT_V(8); PG8_WAIT_L(0); PG8_BAR; PG8_MMA(0, 0, At, B0); PG8_MMA(0, 1, At, B1); PG8_BAR; PG8_SCHED;
;             PG8_LDA(At, 0, 1); PG8_STAGE(PG8_SB(0, 0), b2, voffB); PG8_STAGE(PG8_SB(0, 1), b2 + hstep, voffB); PG8_STAGE(PG8_SA(0, 0), a2, voffA);
;             PG8_WAIT_V(8); PG8_WAIT_L(0); PG8_BAR; PG8_MMA(1, 0, At, B0); PG8_MMA(1, 1, At, B1); PG8_BAR; PG8_SCHED;
;             PG8_LDB(B0, 1, 0); PG8_LDB(B1, 1, 1); PG8_SCHED; PG8_LDA(At, 1, 0); PG8_STAGE(PG8_SA(0, 1), a2 + hstep, voffA);
;             PG8_WAIT_V(8); PG8_WAIT_L(0); PG8_BAR; PG8_MMA(0, 0, At, B0); PG8_MMA(0, 1, At, B1); PG8_BAR; PG8_SCHED;
;             PG8_LDA(At, 1, 1); PG8_STAGE(PG8_SB(1, 0), b3, voffB); PG8_STAGE(PG8_SB(1, 1), b3 + hstep, voffB); PG8_STAGE(PG8_SA(1, 0), a3, voffA);
;             PG8_WAIT_V(8); PG8_WAIT_L(0); PG8_BAR; PG8_MMA(1, 0, At, B0); PG8_MMA(1, 1, At, B1); PG8_BAR; PG8_SCHED;
	v_mfma_f32_16x16x32_bf16 v[62:65], v[142:145], v[178:181], v[62:65]
	v_mfma_f32_16x16x32_bf16 v[62:65], v[146:149], v[182:185], v[62:65]
	v_mfma_f32_16x16x32_bf16 v[58:61], v[150:153], v[178:181], v[58:61]
	v_mfma_f32_16x16x32_bf16 v[58:61], v[154:157], v[182:185], v[58:61]
	v_mfma_f32_16x16x32_bf16 v[42:45], v[150:153], v[186:189], v[42:45]
	v_mfma_f32_16x16x32_bf16 v[42:45], v[154:157], v[190:193], v[42:45]
	v_mfma_f32_16x16x32_bf16 v[46:49], v[142:145], v[186:189], v[46:49]
	v_mfma_f32_16x16x32_bf16 v[46:49], v[146:149], v[190:193], v[46:49]
	v_mfma_f32_16x16x32_bf16 v[30:33], v[142:145], v[194:197], v[30:33]
	v_mfma_f32_16x16x32_bf16 v[30:33], v[146:149], v[198:201], v[30:33]
	v_mfma_f32_16x16x32_bf16 v[26:29], v[150:153], v[194:197], v[26:29]
	v_mfma_f32_16x16x32_bf16 v[26:29], v[154:157], v[198:201], v[26:29]
	v_mfma_f32_16x16x32_bf16 v[10:13], v[150:153], v[202:205], v[10:13]
	v_mfma_f32_16x16x32_bf16 v[10:13], v[154:157], v[206:209], v[10:13]
	v_mfma_f32_16x16x32_bf16 v[14:17], v[142:145], v[202:205], v[14:17]
	v_mfma_f32_16x16x32_bf16 v[14:17], v[146:149], v[206:209], v[14:17]
	s_setprio 0
	s_setprio 1
	v_mfma_f32_16x16x32_bf16 v[54:57], v[162:165], v[178:181], v[54:57]
	v_mfma_f32_16x16x32_bf16 v[54:57], v[166:169], v[182:185], v[54:57]
	v_mfma_f32_16x16x32_bf16 v[50:53], v[170:173], v[178:181], v[50:53]
	v_mfma_f32_16x16x32_bf16 v[50:53], v[174:177], v[182:185], v[50:53]
	v_mfma_f32_16x16x32_bf16 v[34:37], v[170:173], v[186:189], v[34:37]
	v_mfma_f32_16x16x32_bf16 v[34:37], v[174:177], v[190:193], v[34:37]
	v_mfma_f32_16x16x32_bf16 v[38:41], v[162:165], v[186:189], v[38:41]
	v_mfma_f32_16x16x32_bf16 v[38:41], v[166:169], v[190:193], v[38:41]
	v_mfma_f32_16x16x32_bf16 v[22:25], v[162:165], v[194:197], v[22:25]
	v_mfma_f32_16x16x32_bf16 v[22:25], v[166:169], v[198:201], v[22:25]
	v_mfma_f32_16x16x32_bf16 v[18:21], v[170:173], v[194:197], v[18:21]
	v_mfma_f32_16x16x32_bf16 v[18:21], v[174:177], v[198:201], v[18:21]
	v_mfma_f32_16x16x32_bf16 v[2:5], v[170:173], v[202:205], v[2:5]
	v_mfma_f32_16x16x32_bf16 v[2:5], v[174:177], v[206:209], v[2:5]
	v_mfma_f32_16x16x32_bf16 v[6:9], v[162:165], v[202:205], v[6:9]
	v_mfma_f32_16x16x32_bf16 v[6:9], v[166:169], v[206:209], v[6:9]
	s_setprio 0
	s_barrier
	s_add_i32 s41, 0, 0x18000
	v_add_u32_e32 v0, s41, v159
	s_add_i32 s57, 0, 0x1c000
	ds_read_b128 v[142:145], v0
	ds_read_b128 v[146:149], v0 offset:1024
	ds_read_b128 v[150:153], v0 offset:2048
	ds_read_b128 v[154:157], v0 offset:3072
	v_add_u32_e32 v0, s57, v159
	ds_read_b128 v[162:165], v0
	ds_read_b128 v[166:169], v0 offset:1024
	ds_read_b128 v[170:173], v0 offset:2048
	ds_read_b128 v[174:177], v0 offset:3072
	s_add_u32 s30, s30, 0x80000
	s_addc_u32 s31, s31, 0
	s_mov_b32 m0, s47
	v_lshl_add_u64 v[218:219], s[30:31], 0, v[136:137]
	ds_read_b128 v[178:181], v161 offset:32768
	ds_read_b128 v[182:185], v161 offset:33792
	ds_read_b128 v[186:189], v161 offset:34816
	ds_read_b128 v[190:193], v161 offset:35840
	ds_read_b128 v[194:197], v161 offset:36864
	ds_read_b128 v[198:201], v161 offset:37888
	ds_read_b128 v[202:205], v161 offset:38912
	ds_read_b128 v[206:209], v161 offset:39936
	global_load_lds_dwordx4 v[218:219], off
	v_lshl_add_u64 v[218:219], s[30:31], 0, v[132:133]
	s_mov_b32 m0, s48
	s_nop 0
	global_load_lds_dwordx4 v[218:219], off
	s_waitcnt vmcnt(8)
	s_waitcnt lgkmcnt(0)
	s_setprio 1
	s_barrier
	v_mfma_f32_16x16x32_bf16 v[126:129], v[142:145], v[178:181], v[126:129]
	v_mfma_f32_16x16x32_bf16 v[126:129], v[146:149], v[182:185], v[126:129]
	v_mfma_f32_16x16x32_bf16 v[122:125], v[150:153], v[178:181], v[122:125]
	v_mfma_f32_16x16x32_bf16 v[122:125], v[154:157], v[182:185], v[122:125]
	v_mfma_f32_16x16x32_bf16 v[106:109], v[150:153], v[186:189], v[106:109]
	v_mfma_f32_16x16x32_bf16 v[106:109], v[154:157], v[190:193], v[106:109]
	v_mfma_f32_16x16x32_bf16 v[110:113], v[142:145], v[186:189], v[110:113]
	v_mfma_f32_16x16x32_bf16 v[110:113], v[146:149], v[190:193], v[110:113]
	v_mfma_f32_16x16x32_bf16 v[94:97], v[142:145], v[194:197], v[94:97]
	v_mfma_f32_16x16x32_bf16 v[94:97], v[146:149], v[198:201], v[94:97]
	v_mfma_f32_16x16x32_bf16 v[90:93], v[150:153], v[194:197], v[90:93]
	v_mfma_f32_16x16x32_bf16 v[90:93], v[154:157], v[198:201], v[90:93]
	v_mfma_f32_16x16x32_bf16 v[74:77], v[150:153], v[202:205], v[74:77]
	v_mfma_f32_16x16x32_bf16 v[74:77], v[154:157], v[206:209], v[74:77]
	v_mfma_f32_16x16x32_bf16 v[78:81], v[142:145], v[202:205], v[78:81]
	v_mfma_f32_16x16x32_bf16 v[78:81], v[146:149], v[206:209], v[78:81]
	s_setprio 0
	s_setprio 1
	v_mfma_f32_16x16x32_bf16 v[118:121], v[162:165], v[178:181], v[118:121]
	v_mfma_f32_16x16x32_bf16 v[118:121], v[166:169], v[182:185], v[118:121]
	v_mfma_f32_16x16x32_bf16 v[114:117], v[170:173], v[178:181], v[114:117]
	v_mfma_f32_16x16x32_bf16 v[114:117], v[174:177], v[182:185], v[114:117]
	v_mfma_f32_16x16x32_bf16 v[98:101], v[170:173], v[186:189], v[98:101]
	v_mfma_f32_16x16x32_bf16 v[98:101], v[174:177], v[190:193], v[98:101]
	v_mfma_f32_16x16x32_bf16 v[102:105], v[162:165], v[186:189], v[102:105]
	v_mfma_f32_16x16x32_bf16 v[102:105], v[166:169], v[190:193], v[102:105]
	v_mfma_f32_16x16x32_bf16 v[86:89], v[162:165], v[194:197], v[86:89]
	v_mfma_f32_16x16x32_bf16 v[86:89], v[166:169], v[198:201], v[86:89]
	v_mfma_f32_16x16x32_bf16 v[82:85], v[170:173], v[194:197], v[82:85]
	v_mfma_f32_16x16x32_bf16 v[82:85], v[174:177], v[198:201], v[82:85]
	v_mfma_f32_16x16x32_bf16 v[66:69], v[170:173], v[202:205], v[66:69]
	v_mfma_f32_16x16x32_bf16 v[66:69], v[174:177], v[206:209], v[66:69]
	v_mfma_f32_16x16x32_bf16 v[70:73], v[162:165], v[202:205], v[70:73]
	v_mfma_f32_16x16x32_bf16 v[70:73], v[166:169], v[206:209], v[70:73]
	s_setprio 0
	s_barrier
; #define PG8_STAGE(bufoff, gbase, voff) do { _Pragma("unroll") for (int _i = 0; _i < 2; ++_i) \
;         __builtin_amdgcn_global_load_lds((const unsigned*)((const char*)(gbase) + (voff)[_i]), (LAS unsigned*)(lds + (bufoff) + ldsw + _i * 8192), 16, 0, 0); } while (0)
; #define PG8_LDA(dst, b, h) do { _Pragma("unroll") for (int m = 0; m < 4; ++m) _Pragma("unroll") for (int k = 0; k < 2; ++k) dst[m][k] = *(const LAS bf16x8*)(lds + PG8_SA(b, h) + aoff + m * 2048 + k * 1024); } while (0)
; #define PG8_LDB(dst, b, h) do { _Pragma("unroll") for (int n = 0; n < 2; ++n) _Pragma("unroll") for (int k = 0; k < 2; ++k) dst[n][k] = *(const LAS bf16x8*)(lds + PG8_SB(b, h) + boff + n * 2048 + k * 1024); } while (0)
; template <class Epi, class Sched, bool ALIGN_EPI = false, bool SP2 = false>
; __device__ __forceinline__ void gemm_phase(LAS unsigned char* lds, const Gemm g, const Sched& S, const Epi& E) {
;     ...
;         for (int t = 0; t < nt; t += 2) {
;             const bool last = (t == nt - 2);
;             const char* a1 = cA + (size_t)(t + 1) * kstep;
;             const char* a2 = last ? nA : cA + (size_t)(t + 2) * kstep; const char* b2 = last ? nB : cB + (size_t)(t + 2) * kstep;
;             const char* a3 = a2 + kstep; const char* b3 = b2 + kstep;
;             if (last && has_next) S.a_ready(nxt);
;             if constexpr (SP2) {
;             PG8_LDB(B0, 0, 0); PG8_LDB(B1, 0, 1); PG8_SCHED; PG8_LDA(At, 0, 0); PG8_STAGE(PG8_SA(1, 1), a1 + hstep, voffA);
;             PG8_WAIT_V(8); PG8_WAIT_L(0); PG8_BAR; PG8_MMA(0, 0, At, B0); PG8_MMA(0, 1, At, B1); PG8_BAR; PG8_SCHED;
;             PG8_LDA(At, 0, 1); PG8_STAGE(PG8_SB(0, 0), b2, voffB); PG8_STAGE(PG8_SB(0, 1), b2 + hstep, voffB); PG8_STAGE(PG8_SA(0, 0), a2, voffA);
;             PG8_WAIT_V(8); PG8_WAIT_L(0); PG8_BAR; PG8_MMA(1, 0, At, B0); PG8_MMA(1, 1, At, B1); PG8_BAR; PG8_SCHED;
;             PG8_LDB(B0, 1, 0); PG8_LDB(B1, 1, 1); PG8_SCHED; PG8_LDA(At, 1, 0); PG8_STAGE(PG8_SA(0, 1), a2 + hstep, voffA);
;             PG8_WAIT_V(8); PG8_WAIT_L(0); PG8_BAR; PG8_MMA(0, 0, At, B0); PG8_MMA(0, 1, At, B1); PG8_BAR; PG8_SCHED;
;             PG8_LDA(At, 1, 1); PG8_STAGE(PG8_SB(1, 0), b3, voffB); PG8_STAGE(PG8_SB(1, 1), b3 + hstep, voffB); PG8_STAGE(PG8_SA(1, 0), a3, voffA);
;             PG8_WAIT_V(8); PG8_WAIT_L(0); PG8_BAR; PG8_MMA(1, 0, At, B0); PG8_MMA(1, 1, At, B1); PG8_BAR; PG8_SCHED;
	s_add_i32 s30, s41, s9
	v_lshl_add_u64 v[210:211], v[210:211], 0, s[12:13]
	s_mov_b32 m0, s30
	ds_read_b128 v[178:181], v161 offset:49152
	ds_read_b128 v[182:185], v161 offset:50176
	ds_read_b128 v[186:189], v161 offset:51200
	ds_read_b128 v[190:193], v161 offset:52224
	ds_read_b128 v[194:197], v161 offset:53248
	ds_read_b128 v[198:201], v161 offset:54272
	ds_read_b128 v[202:205], v161 offset:55296
	ds_read_b128 v[206:209], v161 offset:56320
	global_load_lds_dwordx4 v[210:211], off
	s_add_i32 m0, s30, 0x2000
	s_add_u32 s28, s28, 0x80080
	v_lshl_add_u64 v[210:211], v[212:213], 0, s[12:13]
	s_addc_u32 s29, s29, 0
	s_add_i32 s30, s57, s9
	global_load_lds_dwordx4 v[210:211], off
	v_lshl_add_u64 v[210:211], s[28:29], 0, v[134:135]
	s_mov_b32 m0, s30
	s_nop 0
	global_load_lds_dwordx4 v[210:211], off
	v_lshl_add_u64 v[210:211], s[28:29], 0, v[130:131]
	s_add_i32 m0, s30, 0x2000
	s_nop 0
	global_load_lds_dwordx4 v[210:211], off
	v_lshl_add_u64 v[210:211], v[214:215], 0, s[12:13]
	s_mov_b32 m0, s53
	s_nop 0
	global_load_lds_dwordx4 v[210:211], off
	v_lshl_add_u64 v[210:211], v[216:217], 0, s[12:13]
	s_mov_b32 m0, s54
	s_nop 0
	global_load_lds_dwordx4 v[210:211], off
	s_waitcnt vmcnt(8)
	s_waitcnt lgkmcnt(0)
	s_setprio 1
	s_barrier
	v_mfma_f32_16x16x32_bf16 v[62:65], v[142:145], v[178:181], v[62:65]
	v_mfma_f32_16x16x32_bf16 v[62:65], v[146:149], v[182:185], v[62:65]
	v_mfma_f32_16x16x32_bf16 v[58:61], v[150:153], v[178:181], v[58:61]
	v_mfma_f32_16x16x32_bf16 v[58:61], v[154:157], v[182:185], v[58:61]
	v_mfma_f32_16x16x32_bf16 v[42:45], v[150:153], v[186:189], v[42:45]
	v_mfma_f32_16x16x32_bf16 v[42:45], v[154:157], v[190:193], v[42:45]
	v_mfma_f32_16x16x32_bf16 v[46:49], v[142:145], v[186:189], v[46:49]
	v_mfma_f32_16x16x32_bf16 v[46:49], v[146:149], v[190:193], v[46:49]
	v_mfma_f32_16x16x32_bf16 v[30:33], v[142:145], v[194:197], v[30:33]
	v_mfma_f32_16x16x32_bf16 v[30:33], v[146:149], v[198:201], v[30:33]
	v_mfma_f32_16x16x32_bf16 v[26:29], v[150:153], v[194:197], v[26:29]
	v_mfma_f32_16x16x32_bf16 v[26:29], v[154:157], v[198:201], v[26:29]
	v_mfma_f32_16x16x32_bf16 v[10:13], v[150:153], v[202:205], v[10:13]
	v_mfma_f32_16x16x32_bf16 v[10:13], v[154:157], v[206:209], v[10:13]
	v_mfma_f32_16x16x32_bf16 v[14:17], v[142:145], v[202:205], v[14:17]
	v_mfma_f32_16x16x32_bf16 v[14:17], v[146:149], v[206:209], v[14:17]
	s_setprio 0
	s_setprio 1
	v_mfma_f32_16x16x32_bf16 v[54:57], v[162:165], v[178:181], v[54:57]
	v_mfma_f32_16x16x32_bf16 v[54:57], v[166:169], v[182:185], v[54:57]
	v_mfma_f32_16x16x32_bf16 v[50:53], v[170:173], v[178:181], v[50:53]
	v_mfma_f32_16x16x32_bf16 v[50:53], v[174:177], v[182:185], v[50:53]
	v_mfma_f32_16x16x32_bf16 v[34:37], v[170:173], v[186:189], v[34:37]
	v_mfma_f32_16x16x32_bf16 v[34:37], v[174:177], v[190:193], v[34:37]
	v_mfma_f32_16x16x32_bf16 v[38:41], v[162:165], v[186:189], v[38:41]
	v_mfma_f32_16x16x32_bf16 v[38:41], v[166:169], v[190:193], v[38:41]
	v_mfma_f32_16x16x32_bf16 v[22:25], v[162:165], v[194:197], v[22:25]
	v_mfma_f32_16x16x32_bf16 v[22:25], v[166:169], v[198:201], v[22:25]
	v_mfma_f32_16x16x32_bf16 v[18:21], v[170:173], v[194:197], v[18:21]
	v_mfma_f32_16x16x32_bf16 v[18:21], v[174:177], v[198:201], v[18:21]
	v_mfma_f32_16x16x32_bf16 v[2:5], v[170:173], v[202:205], v[2:5]
	v_mfma_f32_16x16x32_bf16 v[2:5], v[174:177], v[206:209], v[2:5]
	v_mfma_f32_16x16x32_bf16 v[6:9], v[162:165], v[202:205], v[6:9]
	v_mfma_f32_16x16x32_bf16 v[6:9], v[166:169], v[206:209], v[6:9]
	s_setprio 0
	s_barrier
	s_add_i32 s40, s40, 2
	s_add_u32 s26, s26, 0x100
	s_addc_u32 s27, s27, 0
	s_add_u32 s21, s21, 0x100
	s_addc_u32 s35, s35, 0
	s_cmp_gt_u32 s40, 29
	s_cbranch_scc0 .LBB0_359
	s_and_b64 vcc, exec, s[16:17]
	s_cbranch_vccz .LBB0_362
	s_barrier

; #define PG8_STAGE(bufoff, gbase, voff) do { _Pragma("unroll") for (int _i = 0; _i < 2; ++_i) \
;         __builtin_amdgcn_global_load_lds((const unsigned*)((const char*)(gbase) + (voff)[_i]), (LAS unsigned*)(lds + (bufoff) + ldsw + _i * 8192), 16, 0, 0); } while (0)
; #define PG8_LDA(dst, b, h) do { _Pragma("unroll") for (int m = 0; m < 4; ++m) _Pragma("unroll") for (int k = 0; k < 2; ++k) dst[m][k] = *(const LAS bf16x8*)(lds + PG8_SA(b, h) + aoff + m * 2048 + k * 1024); } while (0)
; #define PG8_LDB(dst, b, h) do { _Pragma("unroll") for (int n = 0; n < 2; ++n) _Pragma("unroll") for (int k = 0; k < 2; ++k) dst[n][k] = *(const LAS bf16x8*)(lds + PG8_SB(b, h) + boff + n * 2048 + k * 1024); } while (0)
; template <class Epi, class Sched, bool ALIGN_EPI = false, bool SP2 = false>
; __device__ __forceinline__ void gemm_phase(LAS unsigned char* lds, const Gemm g, const Sched& S, const Epi& E) {
;     ...
;         for (int t = 0; t < nt; t += 2) {
;             const bool last = (t == nt - 2);
;             const char* a1 = cA + (size_t)(t + 1) * kstep;
;             const char* a2 = last ? nA : cA + (size_t)(t + 2) * kstep; const char* b2 = last ? nB : cB + (size_t)(t + 2) * kstep;
;             const char* a3 = a2 + kstep; const char* b3 = b2 + kstep;
;             if (last && has_next) S.a_ready(nxt);
;             if constexpr (SP2) {
;             PG8_LDB(B0, 0, 0); PG8_LDB(B1, 0, 1); PG8_SCHED; PG8_LDA(At, 0, 0); PG8_STAGE(PG8_SA(1, 1), a1 + hstep, voffA);
;             PG8_WAIT_V(8); PG8_WAIT_L(0); PG8_BAR; PG8_MMA(0, 0, At, B0); PG8_MMA(0, 1, At, B1); PG8_BAR; PG8_SCHED;
;             PG8_LDA(At, 0, 1); PG8_STAGE(PG8_SB(0, 0), b2, voffB); PG8_STAGE(PG8_SB(0, 1), b2 + hstep, voffB); PG8_STAGE(PG8_SA(0, 0), a2, voffA);
;             PG8_WAIT_V(8); PG8_WAIT_L(0); PG8_BAR; PG8_MMA(1, 0, At, B0); PG8_MMA(1, 1, At, B1); PG8_BAR; PG8_SCHED;
;             PG8_LDB(B0, 1, 0); PG8_LDB(B1, 1, 1); PG8_SCHED; PG8_LDA(At, 1, 0); PG8_STAGE(PG8_SA(0, 1), a2 + hstep, voffA);
;             PG8_WAIT_V(8); PG8_WAIT_L(0); PG8_BAR; PG8_MMA(0, 0, At, B0); PG8_MMA(0, 1, At, B1); PG8_BAR; PG8_SCHED;
;             PG8_LDA(At, 1, 1); PG8_STAGE(PG8_SB(1, 0), b3, voffB); PG8_STAGE(PG8_SB(1, 1), b3 + hstep, voffB); PG8_STAGE(PG8_SA(1, 0), a3, voffA);
;             PG8_WAIT_V(8); PG8_WAIT_L(0); PG8_BAR; PG8_MMA(1, 0, At, B0); PG8_MMA(1, 1, At, B1); PG8_BAR; PG8_SCHED;
.LBB0_833:
	s_add_u32 s28, s26, 0xfff80080
	s_addc_u32 s29, s27, -1
	s_add_i32 s53, 0, 0x10000
	s_cmp_eq_u32 s52, 28
	s_cselect_b32 s31, s21, s29
	s_cselect_b32 s30, s48, s28
	s_cselect_b32 s29, s19, s51
	s_cselect_b32 s28, s49, s50
	s_add_i32 s56, 0, 0x14000
	v_add_u32_e32 v134, s53, v247
	v_add_u32_e32 v158, s56, v247
	ds_read_b128 v[106:109], v134
	ds_read_b128 v[110:113], v134 offset:1024
	ds_read_b128 v[122:125], v134 offset:2048
	ds_read_b128 v[134:137], v134 offset:3072
	ds_read_b128 v[146:149], v158
	ds_read_b128 v[150:153], v158 offset:1024
	ds_read_b128 v[154:157], v158 offset:2048
	ds_read_b128 v[158:161], v158 offset:3072
	v_lshl_add_u64 v[204:205], s[26:27], 0, v[200:201]
	s_add_i32 m0, s8, 0xc000
	ds_read_b128 v[162:165], v249
	ds_read_b128 v[166:169], v249 offset:1024
	ds_read_b128 v[170:173], v249 offset:2048
	ds_read_b128 v[174:177], v249 offset:3072
	ds_read_b128 v[178:181], v249 offset:4096
	ds_read_b128 v[182:185], v249 offset:5120
	ds_read_b128 v[186:189], v249 offset:6144
	ds_read_b128 v[190:193], v249 offset:7168
	global_load_lds_dwordx4 v[204:205], off
	v_lshl_add_u64 v[204:205], s[26:27], 0, v[202:203]
	s_add_i32 m0, s8, 0xe000
	s_nop 0
	global_load_lds_dwordx4 v[204:205], off
	s_waitcnt vmcnt(8)
	s_waitcnt lgkmcnt(0)
	s_setprio 1
	s_barrier
	v_mfma_f32_16x16x32_bf16 v[142:145], v[106:109], v[162:165], v[142:145]
	v_mfma_f32_16x16x32_bf16 v[142:145], v[110:113], v[166:169], v[142:145]
	v_mfma_f32_16x16x32_bf16 v[138:141], v[122:125], v[162:165], v[138:141]
	v_mfma_f32_16x16x32_bf16 v[138:141], v[134:137], v[166:169], v[138:141]
	v_mfma_f32_16x16x32_bf16 v[114:117], v[122:125], v[170:173], v[114:117]
	v_mfma_f32_16x16x32_bf16 v[114:117], v[134:137], v[174:177], v[114:117]
	v_mfma_f32_16x16x32_bf16 v[118:121], v[106:109], v[170:173], v[118:121]
	v_mfma_f32_16x16x32_bf16 v[118:121], v[110:113], v[174:177], v[118:121]
	v_mfma_f32_16x16x32_bf16 v[94:97], v[106:109], v[178:181], v[94:97]
	v_mfma_f32_16x16x32_bf16 v[94:97], v[110:113], v[182:185], v[94:97]
	v_mfma_f32_16x16x32_bf16 v[90:93], v[122:125], v[178:181], v[90:93]
	v_mfma_f32_16x16x32_bf16 v[90:93], v[134:137], v[182:185], v[90:93]
	v_mfma_f32_16x16x32_bf16 v[74:77], v[122:125], v[186:189], v[74:77]
	v_mfma_f32_16x16x32_bf16 v[74:77], v[134:137], v[190:193], v[74:77]
	v_mfma_f32_16x16x32_bf16 v[78:81], v[106:109], v[186:189], v[78:81]
	v_mfma_f32_16x16x32_bf16 v[78:81], v[110:113], v[190:193], v[78:81]
	s_setprio 0
	s_setprio 1
	v_mfma_f32_16x16x32_bf16 v[130:133], v[146:149], v[162:165], v[130:133]
	v_mfma_f32_16x16x32_bf16 v[130:133], v[150:153], v[166:169], v[130:133]
	v_mfma_f32_16x16x32_bf16 v[126:129], v[154:157], v[162:165], v[126:129]
	v_mfma_f32_16x16x32_bf16 v[126:129], v[158:161], v[166:169], v[126:129]
	v_mfma_f32_16x16x32_bf16 v[98:101], v[154:157], v[170:173], v[98:101]
	v_mfma_f32_16x16x32_bf16 v[98:101], v[158:161], v[174:177], v[98:101]
	v_mfma_f32_16x16x32_bf16 v[102:105], v[146:149], v[170:173], v[102:105]
	v_mfma_f32_16x16x32_bf16 v[102:105], v[150:153], v[174:177], v[102:105]
	v_mfma_f32_16x16x32_bf16 v[86:89], v[146:149], v[178:181], v[86:89]
	v_mfma_f32_16x16x32_bf16 v[86:89], v[150:153], v[182:185], v[86:89]
	v_mfma_f32_16x16x32_bf16 v[82:85], v[154:157], v[178:181], v[82:85]
	v_mfma_f32_16x16x32_bf16 v[82:85], v[158:161], v[182:185], v[82:85]
	v_mfma_f32_16x16x32_bf16 v[66:69], v[154:157], v[186:189], v[66:69]
	v_mfma_f32_16x16x32_bf16 v[66:69], v[158:161], v[190:193], v[66:69]
	v_mfma_f32_16x16x32_bf16 v[70:73], v[146:149], v[186:189], v[70:73]
	v_mfma_f32_16x16x32_bf16 v[70:73], v[150:153], v[190:193], v[70:73]
	s_setprio 0
	s_barrier
	s_add_i32 s53, s53, s7
	v_lshl_add_u64 v[204:205], s[28:29], 0, v[0:1]
	s_mov_b32 m0, s53
	ds_read_b128 v[162:165], v249 offset:16384
	ds_read_b128 v[166:169], v249 offset:17408
	ds_read_b128 v[170:173], v249 offset:18432
	ds_read_b128 v[174:177], v249 offset:19456
	ds_read_b128 v[178:181], v249 offset:20480
	ds_read_b128 v[182:185], v249 offset:21504
	ds_read_b128 v[186:189], v249 offset:22528
	ds_read_b128 v[190:193], v249 offset:23552
	global_load_lds_dwordx4 v[204:205], off
	s_add_i32 m0, s53, 0x2000
	s_add_u32 s54, s28, 0x80000
	v_lshl_add_u64 v[206:207], s[28:29], 0, v[194:195]
	s_addc_u32 s55, s29, 0
	s_add_i32 s53, s56, s7
	global_load_lds_dwordx4 v[206:207], off
	v_lshl_add_u64 v[208:209], s[54:55], 0, v[0:1]
	s_mov_b32 m0, s53
	v_lshl_add_u64 v[210:211], s[30:31], 0, v[196:197]
	global_load_lds_dwordx4 v[208:209], off
	v_lshl_add_u64 v[208:209], s[54:55], 0, v[194:195]
	s_add_i32 m0, s53, 0x2000
	s_nop 0
	global_load_lds_dwordx4 v[208:209], off
	v_lshl_add_u64 v[208:209], s[30:31], 0, v[198:199]
	s_mov_b32 m0, s8
	s_nop 0
	global_load_lds_dwordx4 v[208:209], off
	s_mov_b32 m0, s9
	s_nop 0
	global_load_lds_dwordx4 v[210:211], off
	s_waitcnt vmcnt(8)
	s_waitcnt lgkmcnt(0)
	s_setprio 1
	s_barrier
; #define PG8_STAGE(bufoff, gbase, voff) do { _Pragma("unroll") for (int _i = 0; _i < 2; ++_i) \
;         __builtin_amdgcn_global_load_lds((const unsigned*)((const char*)(gbase) + (voff)[_i]), (LAS unsigned*)(lds + (bufoff) + ldsw + _i * 8192), 16, 0, 0); } while (0)
; #define PG8_LDA(dst, b, h) do { _Pragma("unroll") for (int m = 0; m < 4; ++m) _Pragma("unroll") for (int k = 0; k < 2; ++k) dst[m][k] = *(const LAS bf16x8*)(lds + PG8_SA(b, h) + aoff + m * 2048 + k * 1024); } while (0)
; #define PG8_LDB(dst, b, h) do { _Pragma("unroll") for (int n = 0; n < 2; ++n) _Pragma("unroll") for (int k = 0; k < 2; ++k) dst[n][k] = *(const LAS bf16x8*)(lds + PG8_SB(b, h) + boff + n * 2048 + k * 1024); } while (0)
; template <class Epi, class Sched, bool ALIGN_EPI = false, bool SP2 = false>
; __device__ __forceinline__ void gemm_phase(LAS unsigned char* lds, const Gemm g, const Sched& S, const Epi& E) {
;     ...
;         for (int t = 0; t < nt; t += 2) {
;             const bool last = (t == nt - 2);
;             const char* a1 = cA + (size_t)(t + 1) * kstep;
;             const char* a2 = last ? nA : cA + (size_t)(t + 2) * kstep; const char* b2 = last ? nB : cB + (size_t)(t + 2) * kstep;
;             const char* a3 = a2 + kstep; const char* b3 = b2 + kstep;
;             if (last && has_next) S.a_ready(nxt);
;             if constexpr (SP2) {
;             PG8_LDB(B0, 0, 0); PG8_LDB(B1, 0, 1); PG8_SCHED; PG8_LDA(At, 0, 0); PG8_STAGE(PG8_SA(1, 1), a1 + hstep, voffA);
;             PG8_WAIT_V(8); PG8_WAIT_L(0); PG8_BAR; PG8_MMA(0, 0, At, B0); PG8_MMA(0, 1, At, B1); PG8_BAR; PG8_SCHED;
;             PG8_LDA(At, 0, 1); PG8_STAGE(PG8_SB(0, 0), b2, voffB); PG8_STAGE(PG8_SB(0, 1), b2 + hstep, voffB); PG8_STAGE(PG8_SA(0, 0), a2, voffA);
;             PG8_WAIT_V(8); PG8_WAIT_L(0); PG8_BAR; PG8_MMA(1, 0, At, B0); PG8_MMA(1, 1, At, B1); PG8_BAR; PG8_SCHED;
;             PG8_LDB(B0, 1, 0); PG8_LDB(B1, 1, 1); PG8_SCHED; PG8_LDA(At, 1, 0); PG8_STAGE(PG8_SA(0, 1), a2 + hstep, voffA);
;             PG8_WAIT_V(8); PG8_WAIT_L(0); PG8_BAR; PG8_MMA(0, 0, At, B0); PG8_MMA(0, 1, At, B1); PG8_BAR; PG8_SCHED;
;             PG8_LDA(At, 1, 1); PG8_STAGE(PG8_SB(1, 0), b3, voffB); PG8_STAGE(PG8_SB(1, 1), b3 + hstep, voffB); PG8_STAGE(PG8_SA(1, 0), a3, voffA);
;             PG8_WAIT_V(8); PG8_WAIT_L(0); PG8_BAR; PG8_MMA(1, 0, At, B0); PG8_MMA(1, 1, At, B1); PG8_BAR; PG8_SCHED;
	v_mfma_f32_16x16x32_bf16 v[62:65], v[106:109], v[162:165], v[62:65]
	v_mfma_f32_16x16x32_bf16 v[62:65], v[110:113], v[166:169], v[62:65]
	v_mfma_f32_16x16x32_bf16 v[58:61], v[122:125], v[162:165], v[58:61]
	v_mfma_f32_16x16x32_bf16 v[58:61], v[134:137], v[166:169], v[58:61]
	v_mfma_f32_16x16x32_bf16 v[42:45], v[122:125], v[170:173], v[42:45]
	v_mfma_f32_16x16x32_bf16 v[42:45], v[134:137], v[174:177], v[42:45]
	v_mfma_f32_16x16x32_bf16 v[46:49], v[106:109], v[170:173], v[46:49]
	v_mfma_f32_16x16x32_bf16 v[46:49], v[110:113], v[174:177], v[46:49]
	v_mfma_f32_16x16x32_bf16 v[30:33], v[106:109], v[178:181], v[30:33]
	v_mfma_f32_16x16x32_bf16 v[30:33], v[110:113], v[182:185], v[30:33]
	v_mfma_f32_16x16x32_bf16 v[26:29], v[122:125], v[178:181], v[26:29]
	v_mfma_f32_16x16x32_bf16 v[26:29], v[134:137], v[182:185], v[26:29]
	v_mfma_f32_16x16x32_bf16 v[10:13], v[122:125], v[186:189], v[10:13]
	v_mfma_f32_16x16x32_bf16 v[10:13], v[134:137], v[190:193], v[10:13]
	v_mfma_f32_16x16x32_bf16 v[14:17], v[106:109], v[186:189], v[14:17]
	v_mfma_f32_16x16x32_bf16 v[14:17], v[110:113], v[190:193], v[14:17]
	s_setprio 0
	s_setprio 1
	v_mfma_f32_16x16x32_bf16 v[54:57], v[146:149], v[162:165], v[54:57]
	v_mfma_f32_16x16x32_bf16 v[54:57], v[150:153], v[166:169], v[54:57]
	v_mfma_f32_16x16x32_bf16 v[50:53], v[154:157], v[162:165], v[50:53]
	v_mfma_f32_16x16x32_bf16 v[50:53], v[158:161], v[166:169], v[50:53]
	v_mfma_f32_16x16x32_bf16 v[34:37], v[154:157], v[170:173], v[34:37]
	v_mfma_f32_16x16x32_bf16 v[34:37], v[158:161], v[174:177], v[34:37]
	v_mfma_f32_16x16x32_bf16 v[38:41], v[146:149], v[170:173], v[38:41]
	v_mfma_f32_16x16x32_bf16 v[38:41], v[150:153], v[174:177], v[38:41]
	v_mfma_f32_16x16x32_bf16 v[22:25], v[146:149], v[178:181], v[22:25]
	v_mfma_f32_16x16x32_bf16 v[22:25], v[150:153], v[182:185], v[22:25]
	v_mfma_f32_16x16x32_bf16 v[18:21], v[154:157], v[178:181], v[18:21]
	v_mfma_f32_16x16x32_bf16 v[18:21], v[158:161], v[182:185], v[18:21]
	v_mfma_f32_16x16x32_bf16 v[2:5], v[154:157], v[186:189], v[2:5]
	v_mfma_f32_16x16x32_bf16 v[2:5], v[158:161], v[190:193], v[2:5]
	v_mfma_f32_16x16x32_bf16 v[6:9], v[146:149], v[186:189], v[6:9]
	v_mfma_f32_16x16x32_bf16 v[6:9], v[150:153], v[190:193], v[6:9]
	s_setprio 0
	s_barrier
	s_add_i32 s53, 0, 0x18000
	s_add_i32 s54, 0, 0x1c000
	v_add_u32_e32 v134, s53, v247
	v_add_u32_e32 v158, s54, v247
	ds_read_b128 v[106:109], v134
	ds_read_b128 v[110:113], v134 offset:1024
	ds_read_b128 v[122:125], v134 offset:2048
	ds_read_b128 v[134:137], v134 offset:3072
	ds_read_b128 v[146:149], v158
	ds_read_b128 v[150:153], v158 offset:1024
	ds_read_b128 v[154:157], v158 offset:2048
	ds_read_b128 v[158:161], v158 offset:3072
	s_add_u32 s30, s30, 0x80000
	s_addc_u32 s31, s31, 0
	s_mov_b32 m0, s35
	v_lshl_add_u64 v[212:213], s[30:31], 0, v[198:199]
	ds_read_b128 v[162:165], v249 offset:32768
	ds_read_b128 v[166:169], v249 offset:33792
	ds_read_b128 v[170:173], v249 offset:34816
	ds_read_b128 v[174:177], v249 offset:35840
	ds_read_b128 v[178:181], v249 offset:36864
	ds_read_b128 v[182:185], v249 offset:37888
	ds_read_b128 v[186:189], v249 offset:38912
	ds_read_b128 v[190:193], v249 offset:39936
	global_load_lds_dwordx4 v[212:213], off
	v_lshl_add_u64 v[212:213], s[30:31], 0, v[196:197]
	s_mov_b32 m0, s42
	s_nop 0
	global_load_lds_dwordx4 v[212:213], off
	s_waitcnt vmcnt(8)
	s_waitcnt lgkmcnt(0)
	s_setprio 1
	s_barrier
	v_mfma_f32_16x16x32_bf16 v[142:145], v[106:109], v[162:165], v[142:145]
	v_mfma_f32_16x16x32_bf16 v[142:145], v[110:113], v[166:169], v[142:145]
	v_mfma_f32_16x16x32_bf16 v[138:141], v[122:125], v[162:165], v[138:141]
	v_mfma_f32_16x16x32_bf16 v[138:141], v[134:137], v[166:169], v[138:141]
	v_mfma_f32_16x16x32_bf16 v[114:117], v[122:125], v[170:173], v[114:117]
	v_mfma_f32_16x16x32_bf16 v[114:117], v[134:137], v[174:177], v[114:117]
	v_mfma_f32_16x16x32_bf16 v[118:121], v[106:109], v[170:173], v[118:121]
	v_mfma_f32_16x16x32_bf16 v[118:121], v[110:113], v[174:177], v[118:121]
	v_mfma_f32_16x16x32_bf16 v[94:97], v[106:109], v[178:181], v[94:97]
	v_mfma_f32_16x16x32_bf16 v[94:97], v[110:113], v[182:185], v[94:97]
	v_mfma_f32_16x16x32_bf16 v[90:93], v[122:125], v[178:181], v[90:93]
	v_mfma_f32_16x16x32_bf16 v[90:93], v[134:137], v[182:185], v[90:93]
	v_mfma_f32_16x16x32_bf16 v[74:77], v[122:125], v[186:189], v[74:77]
	v_mfma_f32_16x16x32_bf16 v[74:77], v[134:137], v[190:193], v[74:77]
	v_mfma_f32_16x16x32_bf16 v[78:81], v[106:109], v[186:189], v[78:81]
	v_mfma_f32_16x16x32_bf16 v[78:81], v[110:113], v[190:193], v[78:81]
	s_setprio 0
	s_setprio 1
	v_mfma_f32_16x16x32_bf16 v[130:133], v[146:149], v[162:165], v[130:133]
	v_mfma_f32_16x16x32_bf16 v[130:133], v[150:153], v[166:169], v[130:133]
	v_mfma_f32_16x16x32_bf16 v[126:129], v[154:157], v[162:165], v[126:129]
	v_mfma_f32_16x16x32_bf16 v[126:129], v[158:161], v[166:169], v[126:129]
	v_mfma_f32_16x16x32_bf16 v[98:101], v[154:157], v[170:173], v[98:101]
	v_mfma_f32_16x16x32_bf16 v[98:101], v[158:161], v[174:177], v[98:101]
	v_mfma_f32_16x16x32_bf16 v[102:105], v[146:149], v[170:173], v[102:105]
	v_mfma_f32_16x16x32_bf16 v[102:105], v[150:153], v[174:177], v[102:105]
	v_mfma_f32_16x16x32_bf16 v[86:89], v[146:149], v[178:181], v[86:89]
	v_mfma_f32_16x16x32_bf16 v[86:89], v[150:153], v[182:185], v[86:89]
	v_mfma_f32_16x16x32_bf16 v[82:85], v[154:157], v[178:181], v[82:85]
	v_mfma_f32_16x16x32_bf16 v[82:85], v[158:161], v[182:185], v[82:85]
	v_mfma_f32_16x16x32_bf16 v[66:69], v[154:157], v[186:189], v[66:69]
	v_mfma_f32_16x16x32_bf16 v[66:69], v[158:161], v[190:193], v[66:69]
	v_mfma_f32_16x16x32_bf16 v[70:73], v[146:149], v[186:189], v[70:73]
	v_mfma_f32_16x16x32_bf16 v[70:73], v[150:153], v[190:193], v[70:73]
	s_setprio 0
	s_barrier
; #define PG8_STAGE(bufoff, gbase, voff) do { _Pragma("unroll") for (int _i = 0; _i < 2; ++_i) \
;         __builtin_amdgcn_global_load_lds((const unsigned*)((const char*)(gbase) + (voff)[_i]), (LAS unsigned*)(lds + (bufoff) + ldsw + _i * 8192), 16, 0, 0); } while (0)
; #define PG8_LDA(dst, b, h) do { _Pragma("unroll") for (int m = 0; m < 4; ++m) _Pragma("unroll") for (int k = 0; k < 2; ++k) dst[m][k] = *(const LAS bf16x8*)(lds + PG8_SA(b, h) + aoff + m * 2048 + k * 1024); } while (0)
; #define PG8_LDB(dst, b, h) do { _Pragma("unroll") for (int n = 0; n < 2; ++n) _Pragma("unroll") for (int k = 0; k < 2; ++k) dst[n][k] = *(const LAS bf16x8*)(lds + PG8_SB(b, h) + boff + n * 2048 + k * 1024); } while (0)
; template <class Epi, class Sched, bool ALIGN_EPI = false, bool SP2 = false>
; __device__ __forceinline__ void gemm_phase(LAS unsigned char* lds, const Gemm g, const Sched& S, const Epi& E) {
;     ...
;         for (int t = 0; t < nt; t += 2) {
;             const bool last = (t == nt - 2);
;             const char* a1 = cA + (size_t)(t + 1) * kstep;
;             const char* a2 = last ? nA : cA + (size_t)(t + 2) * kstep; const char* b2 = last ? nB : cB + (size_t)(t + 2) * kstep;
;             const char* a3 = a2 + kstep; const char* b3 = b2 + kstep;
;             if (last && has_next) S.a_ready(nxt);
;             if constexpr (SP2) {
;             PG8_LDB(B0, 0, 0); PG8_LDB(B1, 0, 1); PG8_SCHED; PG8_LDA(At, 0, 0); PG8_STAGE(PG8_SA(1, 1), a1 + hstep, voffA);
;             PG8_WAIT_V(8); PG8_WAIT_L(0); PG8_BAR; PG8_MMA(0, 0, At, B0); PG8_MMA(0, 1, At, B1); PG8_BAR; PG8_SCHED;
;             PG8_LDA(At, 0, 1); PG8_STAGE(PG8_SB(0, 0), b2, voffB); PG8_STAGE(PG8_SB(0, 1), b2 + hstep, voffB); PG8_STAGE(PG8_SA(0, 0), a2, voffA);
;             PG8_WAIT_V(8); PG8_WAIT_L(0); PG8_BAR; PG8_MMA(1, 0, At, B0); PG8_MMA(1, 1, At, B1); PG8_BAR; PG8_SCHED;
;             PG8_LDB(B0, 1, 0); PG8_LDB(B1, 1, 1); PG8_SCHED; PG8_LDA(At, 1, 0); PG8_STAGE(PG8_SA(0, 1), a2 + hstep, voffA);
;             PG8_WAIT_V(8); PG8_WAIT_L(0); PG8_BAR; PG8_MMA(0, 0, At, B0); PG8_MMA(0, 1, At, B1); PG8_BAR; PG8_SCHED;
;             PG8_LDA(At, 1, 1); PG8_STAGE(PG8_SB(1, 0), b3, voffB); PG8_STAGE(PG8_SB(1, 1), b3 + hstep, voffB); PG8_STAGE(PG8_SA(1, 0), a3, voffA);
;             PG8_WAIT_V(8); PG8_WAIT_L(0); PG8_BAR; PG8_MMA(1, 0, At, B0); PG8_MMA(1, 1, At, B1); PG8_BAR; PG8_SCHED;
	s_add_i32 s30, s53, s7
	v_lshl_add_u64 v[204:205], v[204:205], 0, s[12:13]
	s_mov_b32 m0, s30
	ds_read_b128 v[162:165], v249 offset:49152
	ds_read_b128 v[166:169], v249 offset:50176
	ds_read_b128 v[170:173], v249 offset:51200
	ds_read_b128 v[174:177], v249 offset:52224
	ds_read_b128 v[178:181], v249 offset:53248
	ds_read_b128 v[182:185], v249 offset:54272
	ds_read_b128 v[186:189], v249 offset:55296
	ds_read_b128 v[190:193], v249 offset:56320
	global_load_lds_dwordx4 v[204:205], off
	s_add_i32 m0, s30, 0x2000
	s_add_u32 s28, s28, 0x80080
	v_lshl_add_u64 v[204:205], v[206:207], 0, s[12:13]
	s_addc_u32 s29, s29, 0
	s_add_i32 s30, s54, s7
	global_load_lds_dwordx4 v[204:205], off
	v_lshl_add_u64 v[204:205], s[28:29], 0, v[0:1]
	s_mov_b32 m0, s30
	s_nop 0
	global_load_lds_dwordx4 v[204:205], off
	v_lshl_add_u64 v[204:205], s[28:29], 0, v[194:195]
	s_add_i32 m0, s30, 0x2000
	s_nop 0
	global_load_lds_dwordx4 v[204:205], off
	v_lshl_add_u64 v[204:205], v[208:209], 0, s[12:13]
	s_mov_b32 m0, s43
	s_nop 0
	global_load_lds_dwordx4 v[204:205], off
	v_lshl_add_u64 v[204:205], v[210:211], 0, s[12:13]
	s_mov_b32 m0, s44
	s_nop 0
	global_load_lds_dwordx4 v[204:205], off
	s_waitcnt vmcnt(8)
	s_waitcnt lgkmcnt(0)
	s_setprio 1
	s_barrier
	v_mfma_f32_16x16x32_bf16 v[62:65], v[106:109], v[162:165], v[62:65]
	v_mfma_f32_16x16x32_bf16 v[62:65], v[110:113], v[166:169], v[62:65]
	v_mfma_f32_16x16x32_bf16 v[58:61], v[122:125], v[162:165], v[58:61]
	v_mfma_f32_16x16x32_bf16 v[58:61], v[134:137], v[166:169], v[58:61]
	v_mfma_f32_16x16x32_bf16 v[42:45], v[122:125], v[170:173], v[42:45]
	v_mfma_f32_16x16x32_bf16 v[42:45], v[134:137], v[174:177], v[42:45]
	v_mfma_f32_16x16x32_bf16 v[46:49], v[106:109], v[170:173], v[46:49]
	v_mfma_f32_16x16x32_bf16 v[46:49], v[110:113], v[174:177], v[46:49]
	v_mfma_f32_16x16x32_bf16 v[30:33], v[106:109], v[178:181], v[30:33]
	v_mfma_f32_16x16x32_bf16 v[30:33], v[110:113], v[182:185], v[30:33]
	v_mfma_f32_16x16x32_bf16 v[26:29], v[122:125], v[178:181], v[26:29]
	v_mfma_f32_16x16x32_bf16 v[26:29], v[134:137], v[182:185], v[26:29]
	v_mfma_f32_16x16x32_bf16 v[10:13], v[122:125], v[186:189], v[10:13]
	v_mfma_f32_16x16x32_bf16 v[10:13], v[134:137], v[190:193], v[10:13]
	v_mfma_f32_16x16x32_bf16 v[14:17], v[106:109], v[186:189], v[14:17]
	v_mfma_f32_16x16x32_bf16 v[14:17], v[110:113], v[190:193], v[14:17]
	s_setprio 0
	s_setprio 1
	v_mfma_f32_16x16x32_bf16 v[54:57], v[146:149], v[162:165], v[54:57]
	v_mfma_f32_16x16x32_bf16 v[54:57], v[150:153], v[166:169], v[54:57]
	v_mfma_f32_16x16x32_bf16 v[50:53], v[154:157], v[162:165], v[50:53]
	v_mfma_f32_16x16x32_bf16 v[50:53], v[158:161], v[166:169], v[50:53]
	v_mfma_f32_16x16x32_bf16 v[34:37], v[154:157], v[170:173], v[34:37]
	v_mfma_f32_16x16x32_bf16 v[34:37], v[158:161], v[174:177], v[34:37]
	v_mfma_f32_16x16x32_bf16 v[38:41], v[146:149], v[170:173], v[38:41]
	v_mfma_f32_16x16x32_bf16 v[38:41], v[150:153], v[174:177], v[38:41]
	v_mfma_f32_16x16x32_bf16 v[22:25], v[146:149], v[178:181], v[22:25]
	v_mfma_f32_16x16x32_bf16 v[22:25], v[150:153], v[182:185], v[22:25]
	v_mfma_f32_16x16x32_bf16 v[18:21], v[154:157], v[178:181], v[18:21]
	v_mfma_f32_16x16x32_bf16 v[18:21], v[158:161], v[182:185], v[18:21]
	v_mfma_f32_16x16x32_bf16 v[2:5], v[154:157], v[186:189], v[2:5]
	v_mfma_f32_16x16x32_bf16 v[2:5], v[158:161], v[190:193], v[2:5]
	v_mfma_f32_16x16x32_bf16 v[6:9], v[146:149], v[186:189], v[6:9]
	v_mfma_f32_16x16x32_bf16 v[6:9], v[150:153], v[190:193], v[6:9]
	s_setprio 0
	s_barrier
	s_add_i32 s52, s52, 2
	s_add_u32 s26, s26, 0x100
	s_addc_u32 s27, s27, 0
	s_add_u32 s50, s50, 0x100
	s_addc_u32 s51, s51, 0
	s_cmp_gt_u32 s52, 29
	s_cbranch_scc0 .LBB0_833
	s_and_b64 vcc, exec, s[16:17]
	s_cbranch_vccz .LBB0_836
	s_barrier

; #define PG8_STAGE(bufoff, gbase, voff) do { _Pragma("unroll") for (int _i = 0; _i < 2; ++_i) \
;         __builtin_amdgcn_global_load_lds((const unsigned*)((const char*)(gbase) + (voff)[_i]), (LAS unsigned*)(lds + (bufoff) + ldsw + _i * 8192), 16, 0, 0); } while (0)
; #define PG8_LDA(dst, b, h) do { _Pragma("unroll") for (int m = 0; m < 4; ++m) _Pragma("unroll") for (int k = 0; k < 2; ++k) dst[m][k] = *(const LAS bf16x8*)(lds + PG8_SA(b, h) + aoff + m * 2048 + k * 1024); } while (0)
; #define PG8_LDB(dst, b, h) do { _Pragma("unroll") for (int n = 0; n < 2; ++n) _Pragma("unroll") for (int k = 0; k < 2; ++k) dst[n][k] = *(const LAS bf16x8*)(lds + PG8_SB(b, h) + boff + n * 2048 + k * 1024); } while (0)
; template <class Epi, class Sched, bool ALIGN_EPI = false, bool SP2 = false>
; __device__ __forceinline__ void gemm_phase(LAS unsigned char* lds, const Gemm g, const Sched& S, const Epi& E) {
;     ...
;         for (int t = 0; t < nt; t += 2) {
;             const bool last = (t == nt - 2);
;             const char* a1 = cA + (size_t)(t + 1) * kstep;
;             const char* a2 = last ? nA : cA + (size_t)(t + 2) * kstep; const char* b2 = last ? nB : cB + (size_t)(t + 2) * kstep;
;             const char* a3 = a2 + kstep; const char* b3 = b2 + kstep;
;             if (last && has_next) S.a_ready(nxt);
;             if constexpr (SP2) {
;             PG8_LDB(B0, 0, 0); PG8_LDB(B1, 0, 1); PG8_SCHED; PG8_LDA(At, 0, 0); PG8_STAGE(PG8_SA(1, 1), a1 + hstep, voffA);
;             PG8_WAIT_V(8); PG8_WAIT_L(0); PG8_BAR; PG8_MMA(0, 0, At, B0); PG8_MMA(0, 1, At, B1); PG8_BAR; PG8_SCHED;
;             PG8_LDA(At, 0, 1); PG8_STAGE(PG8_SB(0, 0), b2, voffB); PG8_STAGE(PG8_SB(0, 1), b2 + hstep, voffB); PG8_STAGE(PG8_SA(0, 0), a2, voffA);
;             PG8_WAIT_V(8); PG8_WAIT_L(0); PG8_BAR; PG8_MMA(1, 0, At, B0); PG8_MMA(1, 1, At, B1); PG8_BAR; PG8_SCHED;
;             PG8_LDB(B0, 1, 0); PG8_LDB(B1, 1, 1); PG8_SCHED; PG8_LDA(At, 1, 0); PG8_STAGE(PG8_SA(0, 1), a2 + hstep, voffA);
;             PG8_WAIT_V(8); PG8_WAIT_L(0); PG8_BAR; PG8_MMA(0, 0, At, B0); PG8_MMA(0, 1, At, B1); PG8_BAR; PG8_SCHED;
;             PG8_LDA(At, 1, 1); PG8_STAGE(PG8_SB(1, 0), b3, voffB); PG8_STAGE(PG8_SB(1, 1), b3 + hstep, voffB); PG8_STAGE(PG8_SA(1, 0), a3, voffA);
;             PG8_WAIT_V(8); PG8_WAIT_L(0); PG8_BAR; PG8_MMA(1, 0, At, B0); PG8_MMA(1, 1, At, B1); PG8_BAR; PG8_SCHED;
.LBB0_924:
	s_add_u32 s28, s26, 0xfff80080
	s_addc_u32 s29, s27, -1
	s_add_i32 s51, 0, 0x10000
	s_cmp_eq_u32 s50, 28
	s_cselect_b32 s31, s7, s29
	s_cselect_b32 s30, s8, s28
	v_add_u32_e32 v148, s51, v151
	s_cselect_b32 s29, s19, s49
	s_cselect_b32 s28, s21, s35
	s_add_i32 s54, 0, 0x14000
	ds_read_b128 v[140:143], v148
	ds_read_b128 v[144:147], v148 offset:1024
	ds_read_b128 v[156:159], v148 offset:2048
	ds_read_b128 v[160:163], v148 offset:3072
	v_add_u32_e32 v148, s54, v151
	ds_read_b128 v[164:167], v148
	ds_read_b128 v[168:171], v148 offset:1024
	ds_read_b128 v[172:175], v148 offset:2048
	ds_read_b128 v[176:179], v148 offset:3072
	v_lshl_add_u64 v[212:213], s[26:27], 0, v[136:137]
	s_add_i32 m0, s42, 0xc000
	ds_read_b128 v[180:183], v155
	ds_read_b128 v[184:187], v155 offset:1024
	ds_read_b128 v[188:191], v155 offset:2048
	ds_read_b128 v[192:195], v155 offset:3072
	ds_read_b128 v[196:199], v155 offset:4096
	ds_read_b128 v[200:203], v155 offset:5120
	ds_read_b128 v[204:207], v155 offset:6144
	ds_read_b128 v[208:211], v155 offset:7168
	global_load_lds_dwordx4 v[212:213], off
	v_lshl_add_u64 v[212:213], s[26:27], 0, v[138:139]
	s_add_i32 m0, s42, 0xe000
	s_nop 0
	global_load_lds_dwordx4 v[212:213], off
	s_waitcnt vmcnt(8)
	s_waitcnt lgkmcnt(0)
	s_setprio 1
	s_barrier
	v_mfma_f32_16x16x32_bf16 v[126:129], v[140:143], v[180:183], v[126:129]
	v_mfma_f32_16x16x32_bf16 v[126:129], v[144:147], v[184:187], v[126:129]
	v_mfma_f32_16x16x32_bf16 v[122:125], v[156:159], v[180:183], v[122:125]
	v_mfma_f32_16x16x32_bf16 v[122:125], v[160:163], v[184:187], v[122:125]
	v_mfma_f32_16x16x32_bf16 v[106:109], v[156:159], v[188:191], v[106:109]
	v_mfma_f32_16x16x32_bf16 v[106:109], v[160:163], v[192:195], v[106:109]
	v_mfma_f32_16x16x32_bf16 v[110:113], v[140:143], v[188:191], v[110:113]
	v_mfma_f32_16x16x32_bf16 v[110:113], v[144:147], v[192:195], v[110:113]
	v_mfma_f32_16x16x32_bf16 v[94:97], v[140:143], v[196:199], v[94:97]
	v_mfma_f32_16x16x32_bf16 v[94:97], v[144:147], v[200:203], v[94:97]
	v_mfma_f32_16x16x32_bf16 v[90:93], v[156:159], v[196:199], v[90:93]
	v_mfma_f32_16x16x32_bf16 v[90:93], v[160:163], v[200:203], v[90:93]
	v_mfma_f32_16x16x32_bf16 v[74:77], v[156:159], v[204:207], v[74:77]
	v_mfma_f32_16x16x32_bf16 v[74:77], v[160:163], v[208:211], v[74:77]
	v_mfma_f32_16x16x32_bf16 v[78:81], v[140:143], v[204:207], v[78:81]
	v_mfma_f32_16x16x32_bf16 v[78:81], v[144:147], v[208:211], v[78:81]
	s_setprio 0
	s_setprio 1
	v_mfma_f32_16x16x32_bf16 v[118:121], v[164:167], v[180:183], v[118:121]
	v_mfma_f32_16x16x32_bf16 v[118:121], v[168:171], v[184:187], v[118:121]
	v_mfma_f32_16x16x32_bf16 v[114:117], v[172:175], v[180:183], v[114:117]
	v_mfma_f32_16x16x32_bf16 v[114:117], v[176:179], v[184:187], v[114:117]
	v_mfma_f32_16x16x32_bf16 v[98:101], v[172:175], v[188:191], v[98:101]
	v_mfma_f32_16x16x32_bf16 v[98:101], v[176:179], v[192:195], v[98:101]
	v_mfma_f32_16x16x32_bf16 v[102:105], v[164:167], v[188:191], v[102:105]
	v_mfma_f32_16x16x32_bf16 v[102:105], v[168:171], v[192:195], v[102:105]
	v_mfma_f32_16x16x32_bf16 v[86:89], v[164:167], v[196:199], v[86:89]
	v_mfma_f32_16x16x32_bf16 v[86:89], v[168:171], v[200:203], v[86:89]
	v_mfma_f32_16x16x32_bf16 v[82:85], v[172:175], v[196:199], v[82:85]
	v_mfma_f32_16x16x32_bf16 v[82:85], v[176:179], v[200:203], v[82:85]
	v_mfma_f32_16x16x32_bf16 v[66:69], v[172:175], v[204:207], v[66:69]
	v_mfma_f32_16x16x32_bf16 v[66:69], v[176:179], v[208:211], v[66:69]
	v_mfma_f32_16x16x32_bf16 v[70:73], v[164:167], v[204:207], v[70:73]
	v_mfma_f32_16x16x32_bf16 v[70:73], v[168:171], v[208:211], v[70:73]
	s_setprio 0
	s_barrier
	s_add_i32 s51, s51, s41
	v_lshl_add_u64 v[212:213], s[28:29], 0, v[0:1]
	s_mov_b32 m0, s51
	ds_read_b128 v[180:183], v155 offset:16384
	ds_read_b128 v[184:187], v155 offset:17408
	ds_read_b128 v[188:191], v155 offset:18432
	ds_read_b128 v[192:195], v155 offset:19456
	ds_read_b128 v[196:199], v155 offset:20480
	ds_read_b128 v[200:203], v155 offset:21504
	ds_read_b128 v[204:207], v155 offset:22528
	ds_read_b128 v[208:211], v155 offset:23552
	global_load_lds_dwordx4 v[212:213], off
	s_add_i32 m0, s51, 0x2000
	s_add_u32 s52, s28, 0x80000
	v_lshl_add_u64 v[214:215], s[28:29], 0, v[130:131]
	s_addc_u32 s53, s29, 0
	s_add_i32 s51, s54, s41
	global_load_lds_dwordx4 v[214:215], off
	v_lshl_add_u64 v[216:217], s[52:53], 0, v[0:1]
	s_mov_b32 m0, s51
	v_lshl_add_u64 v[218:219], s[30:31], 0, v[132:133]
	global_load_lds_dwordx4 v[216:217], off
	v_lshl_add_u64 v[216:217], s[52:53], 0, v[130:131]
	s_add_i32 m0, s51, 0x2000
	s_nop 0
	global_load_lds_dwordx4 v[216:217], off
	v_lshl_add_u64 v[216:217], s[30:31], 0, v[134:135]
	s_mov_b32 m0, s42
	s_nop 0
	global_load_lds_dwordx4 v[216:217], off
	s_mov_b32 m0, s43
	s_nop 0
	global_load_lds_dwordx4 v[218:219], off
	s_waitcnt vmcnt(8)
	s_waitcnt lgkmcnt(0)
	s_setprio 1
	s_barrier
; #define PG8_STAGE(bufoff, gbase, voff) do { _Pragma("unroll") for (int _i = 0; _i < 2; ++_i) \
;         __builtin_amdgcn_global_load_lds((const unsigned*)((const char*)(gbase) + (voff)[_i]), (LAS unsigned*)(lds + (bufoff) + ldsw + _i * 8192), 16, 0, 0); } while (0)
; #define PG8_LDA(dst, b, h) do { _Pragma("unroll") for (int m = 0; m < 4; ++m) _Pragma("unroll") for (int k = 0; k < 2; ++k) dst[m][k] = *(const LAS bf16x8*)(lds + PG8_SA(b, h) + aoff + m * 2048 + k * 1024); } while (0)
; #define PG8_LDB(dst, b, h) do { _Pragma("unroll") for (int n = 0; n < 2; ++n) _Pragma("unroll") for (int k = 0; k < 2; ++k) dst[n][k] = *(const LAS bf16x8*)(lds + PG8_SB(b, h) + boff + n * 2048 + k * 1024); } while (0)
; template <class Epi, class Sched, bool ALIGN_EPI = false, bool SP2 = false>
; __device__ __forceinline__ void gemm_phase(LAS unsigned char* lds, const Gemm g, const Sched& S, const Epi& E) {
;     ...
;         for (int t = 0; t < nt; t += 2) {
;             const bool last = (t == nt - 2);
;             const char* a1 = cA + (size_t)(t + 1) * kstep;
;             const char* a2 = last ? nA : cA + (size_t)(t + 2) * kstep; const char* b2 = last ? nB : cB + (size_t)(t + 2) * kstep;
;             const char* a3 = a2 + kstep; const char* b3 = b2 + kstep;
;             if (last && has_next) S.a_ready(nxt);
;             if constexpr (SP2) {
;             PG8_LDB(B0, 0, 0); PG8_LDB(B1, 0, 1); PG8_SCHED; PG8_LDA(At, 0, 0); PG8_STAGE(PG8_SA(1, 1), a1 + hstep, voffA);
;             PG8_WAIT_V(8); PG8_WAIT_L(0); PG8_BAR; PG8_MMA(0, 0, At, B0); PG8_MMA(0, 1, At, B1); PG8_BAR; PG8_SCHED;
;             PG8_LDA(At, 0, 1); PG8_STAGE(PG8_SB(0, 0), b2, voffB); PG8_STAGE(PG8_SB(0, 1), b2 + hstep, voffB); PG8_STAGE(PG8_SA(0, 0), a2, voffA);
;             PG8_WAIT_V(8); PG8_WAIT_L(0); PG8_BAR; PG8_MMA(1, 0, At, B0); PG8_MMA(1, 1, At, B1); PG8_BAR; PG8_SCHED;
;             PG8_LDB(B0, 1, 0); PG8_LDB(B1, 1, 1); PG8_SCHED; PG8_LDA(At, 1, 0); PG8_STAGE(PG8_SA(0, 1), a2 + hstep, voffA);
;             PG8_WAIT_V(8); PG8_WAIT_L(0); PG8_BAR; PG8_MMA(0, 0, At, B0); PG8_MMA(0, 1, At, B1); PG8_BAR; PG8_SCHED;
;             PG8_LDA(At, 1, 1); PG8_STAGE(PG8_SB(1, 0), b3, voffB); PG8_STAGE(PG8_SB(1, 1), b3 + hstep, voffB); PG8_STAGE(PG8_SA(1, 0), a3, voffA);
;             PG8_WAIT_V(8); PG8_WAIT_L(0); PG8_BAR; PG8_MMA(1, 0, At, B0); PG8_MMA(1, 1, At, B1); PG8_BAR; PG8_SCHED;
	v_mfma_f32_16x16x32_bf16 v[62:65], v[140:143], v[180:183], v[62:65]
	v_mfma_f32_16x16x32_bf16 v[62:65], v[144:147], v[184:187], v[62:65]
	v_mfma_f32_16x16x32_bf16 v[58:61], v[156:159], v[180:183], v[58:61]
	v_mfma_f32_16x16x32_bf16 v[58:61], v[160:163], v[184:187], v[58:61]
	v_mfma_f32_16x16x32_bf16 v[42:45], v[156:159], v[188:191], v[42:45]
	v_mfma_f32_16x16x32_bf16 v[42:45], v[160:163], v[192:195], v[42:45]
	v_mfma_f32_16x16x32_bf16 v[46:49], v[140:143], v[188:191], v[46:49]
	v_mfma_f32_16x16x32_bf16 v[46:49], v[144:147], v[192:195], v[46:49]
	v_mfma_f32_16x16x32_bf16 v[30:33], v[140:143], v[196:199], v[30:33]
	v_mfma_f32_16x16x32_bf16 v[30:33], v[144:147], v[200:203], v[30:33]
	v_mfma_f32_16x16x32_bf16 v[26:29], v[156:159], v[196:199], v[26:29]
	v_mfma_f32_16x16x32_bf16 v[26:29], v[160:163], v[200:203], v[26:29]
	v_mfma_f32_16x16x32_bf16 v[10:13], v[156:159], v[204:207], v[10:13]
	v_mfma_f32_16x16x32_bf16 v[10:13], v[160:163], v[208:211], v[10:13]
	v_mfma_f32_16x16x32_bf16 v[14:17], v[140:143], v[204:207], v[14:17]
	v_mfma_f32_16x16x32_bf16 v[14:17], v[144:147], v[208:211], v[14:17]
	s_setprio 0
	s_setprio 1
	v_mfma_f32_16x16x32_bf16 v[54:57], v[164:167], v[180:183], v[54:57]
	v_mfma_f32_16x16x32_bf16 v[54:57], v[168:171], v[184:187], v[54:57]
	v_mfma_f32_16x16x32_bf16 v[50:53], v[172:175], v[180:183], v[50:53]
	v_mfma_f32_16x16x32_bf16 v[50:53], v[176:179], v[184:187], v[50:53]
	v_mfma_f32_16x16x32_bf16 v[34:37], v[172:175], v[188:191], v[34:37]
	v_mfma_f32_16x16x32_bf16 v[34:37], v[176:179], v[192:195], v[34:37]
	v_mfma_f32_16x16x32_bf16 v[38:41], v[164:167], v[188:191], v[38:41]
	v_mfma_f32_16x16x32_bf16 v[38:41], v[168:171], v[192:195], v[38:41]
	v_mfma_f32_16x16x32_bf16 v[22:25], v[164:167], v[196:199], v[22:25]
	v_mfma_f32_16x16x32_bf16 v[22:25], v[168:171], v[200:203], v[22:25]
	v_mfma_f32_16x16x32_bf16 v[18:21], v[172:175], v[196:199], v[18:21]
	v_mfma_f32_16x16x32_bf16 v[18:21], v[176:179], v[200:203], v[18:21]
	v_mfma_f32_16x16x32_bf16 v[2:5], v[172:175], v[204:207], v[2:5]
	v_mfma_f32_16x16x32_bf16 v[2:5], v[176:179], v[208:211], v[2:5]
	v_mfma_f32_16x16x32_bf16 v[6:9], v[164:167], v[204:207], v[6:9]
	v_mfma_f32_16x16x32_bf16 v[6:9], v[168:171], v[208:211], v[6:9]
	s_setprio 0
	s_barrier
	s_add_i32 s51, 0, 0x18000
	v_add_u32_e32 v148, s51, v151
	s_add_i32 s52, 0, 0x1c000
	ds_read_b128 v[140:143], v148
	ds_read_b128 v[144:147], v148 offset:1024
	ds_read_b128 v[156:159], v148 offset:2048
	ds_read_b128 v[160:163], v148 offset:3072
	v_add_u32_e32 v148, s52, v151
	ds_read_b128 v[164:167], v148
	ds_read_b128 v[168:171], v148 offset:1024
	ds_read_b128 v[172:175], v148 offset:2048
	ds_read_b128 v[176:179], v148 offset:3072
	s_add_u32 s30, s30, 0x80000
	s_addc_u32 s31, s31, 0
	s_mov_b32 m0, s44
	v_lshl_add_u64 v[220:221], s[30:31], 0, v[134:135]
	ds_read_b128 v[180:183], v155 offset:32768
	ds_read_b128 v[184:187], v155 offset:33792
	ds_read_b128 v[188:191], v155 offset:34816
	ds_read_b128 v[192:195], v155 offset:35840
	ds_read_b128 v[196:199], v155 offset:36864
	ds_read_b128 v[200:203], v155 offset:37888
	ds_read_b128 v[204:207], v155 offset:38912
	ds_read_b128 v[208:211], v155 offset:39936
	global_load_lds_dwordx4 v[220:221], off
	v_lshl_add_u64 v[220:221], s[30:31], 0, v[132:133]
	s_mov_b32 m0, s45
	s_nop 0
	global_load_lds_dwordx4 v[220:221], off
	s_waitcnt vmcnt(8)
	s_waitcnt lgkmcnt(0)
	s_setprio 1
	s_barrier
	v_mfma_f32_16x16x32_bf16 v[126:129], v[140:143], v[180:183], v[126:129]
	v_mfma_f32_16x16x32_bf16 v[126:129], v[144:147], v[184:187], v[126:129]
	v_mfma_f32_16x16x32_bf16 v[122:125], v[156:159], v[180:183], v[122:125]
	v_mfma_f32_16x16x32_bf16 v[122:125], v[160:163], v[184:187], v[122:125]
	v_mfma_f32_16x16x32_bf16 v[106:109], v[156:159], v[188:191], v[106:109]
	v_mfma_f32_16x16x32_bf16 v[106:109], v[160:163], v[192:195], v[106:109]
	v_mfma_f32_16x16x32_bf16 v[110:113], v[140:143], v[188:191], v[110:113]
	v_mfma_f32_16x16x32_bf16 v[110:113], v[144:147], v[192:195], v[110:113]
	v_mfma_f32_16x16x32_bf16 v[94:97], v[140:143], v[196:199], v[94:97]
	v_mfma_f32_16x16x32_bf16 v[94:97], v[144:147], v[200:203], v[94:97]
	v_mfma_f32_16x16x32_bf16 v[90:93], v[156:159], v[196:199], v[90:93]
	v_mfma_f32_16x16x32_bf16 v[90:93], v[160:163], v[200:203], v[90:93]
	v_mfma_f32_16x16x32_bf16 v[74:77], v[156:159], v[204:207], v[74:77]
	v_mfma_f32_16x16x32_bf16 v[74:77], v[160:163], v[208:211], v[74:77]
	v_mfma_f32_16x16x32_bf16 v[78:81], v[140:143], v[204:207], v[78:81]
	v_mfma_f32_16x16x32_bf16 v[78:81], v[144:147], v[208:211], v[78:81]
	s_setprio 0
	s_setprio 1
	v_mfma_f32_16x16x32_bf16 v[118:121], v[164:167], v[180:183], v[118:121]
	v_mfma_f32_16x16x32_bf16 v[118:121], v[168:171], v[184:187], v[118:121]
	v_mfma_f32_16x16x32_bf16 v[114:117], v[172:175], v[180:183], v[114:117]
	v_mfma_f32_16x16x32_bf16 v[114:117], v[176:179], v[184:187], v[114:117]
	v_mfma_f32_16x16x32_bf16 v[98:101], v[172:175], v[188:191], v[98:101]
	v_mfma_f32_16x16x32_bf16 v[98:101], v[176:179], v[192:195], v[98:101]
	v_mfma_f32_16x16x32_bf16 v[102:105], v[164:167], v[188:191], v[102:105]
	v_mfma_f32_16x16x32_bf16 v[102:105], v[168:171], v[192:195], v[102:105]
	v_mfma_f32_16x16x32_bf16 v[86:89], v[164:167], v[196:199], v[86:89]
	v_mfma_f32_16x16x32_bf16 v[86:89], v[168:171], v[200:203], v[86:89]
	v_mfma_f32_16x16x32_bf16 v[82:85], v[172:175], v[196:199], v[82:85]
	v_mfma_f32_16x16x32_bf16 v[82:85], v[176:179], v[200:203], v[82:85]
	v_mfma_f32_16x16x32_bf16 v[66:69], v[172:175], v[204:207], v[66:69]
	v_mfma_f32_16x16x32_bf16 v[66:69], v[176:179], v[208:211], v[66:69]
	v_mfma_f32_16x16x32_bf16 v[70:73], v[164:167], v[204:207], v[70:73]
	v_mfma_f32_16x16x32_bf16 v[70:73], v[168:171], v[208:211], v[70:73]
	s_setprio 0
	s_barrier
; #define PG8_STAGE(bufoff, gbase, voff) do { _Pragma("unroll") for (int _i = 0; _i < 2; ++_i) \
;         __builtin_amdgcn_global_load_lds((const unsigned*)((const char*)(gbase) + (voff)[_i]), (LAS unsigned*)(lds + (bufoff) + ldsw + _i * 8192), 16, 0, 0); } while (0)
; #define PG8_LDA(dst, b, h) do { _Pragma("unroll") for (int m = 0; m < 4; ++m) _Pragma("unroll") for (int k = 0; k < 2; ++k) dst[m][k] = *(const LAS bf16x8*)(lds + PG8_SA(b, h) + aoff + m * 2048 + k * 1024); } while (0)
; #define PG8_LDB(dst, b, h) do { _Pragma("unroll") for (int n = 0; n < 2; ++n) _Pragma("unroll") for (int k = 0; k < 2; ++k) dst[n][k] = *(const LAS bf16x8*)(lds + PG8_SB(b, h) + boff + n * 2048 + k * 1024); } while (0)
; template <class Epi, class Sched, bool ALIGN_EPI = false, bool SP2 = false>
; __device__ __forceinline__ void gemm_phase(LAS unsigned char* lds, const Gemm g, const Sched& S, const Epi& E) {
;     ...
;         for (int t = 0; t < nt; t += 2) {
;             const bool last = (t == nt - 2);
;             const char* a1 = cA + (size_t)(t + 1) * kstep;
;             const char* a2 = last ? nA : cA + (size_t)(t + 2) * kstep; const char* b2 = last ? nB : cB + (size_t)(t + 2) * kstep;
;             const char* a3 = a2 + kstep; const char* b3 = b2 + kstep;
;             if (last && has_next) S.a_ready(nxt);
;             if constexpr (SP2) {
;             PG8_LDB(B0, 0, 0); PG8_LDB(B1, 0, 1); PG8_SCHED; PG8_LDA(At, 0, 0); PG8_STAGE(PG8_SA(1, 1), a1 + hstep, voffA);
;             PG8_WAIT_V(8); PG8_WAIT_L(0); PG8_BAR; PG8_MMA(0, 0, At, B0); PG8_MMA(0, 1, At, B1); PG8_BAR; PG8_SCHED;
;             PG8_LDA(At, 0, 1); PG8_STAGE(PG8_SB(0, 0), b2, voffB); PG8_STAGE(PG8_SB(0, 1), b2 + hstep, voffB); PG8_STAGE(PG8_SA(0, 0), a2, voffA);
;             PG8_WAIT_V(8); PG8_WAIT_L(0); PG8_BAR; PG8_MMA(1, 0, At, B0); PG8_MMA(1, 1, At, B1); PG8_BAR; PG8_SCHED;
;             PG8_LDB(B0, 1, 0); PG8_LDB(B1, 1, 1); PG8_SCHED; PG8_LDA(At, 1, 0); PG8_STAGE(PG8_SA(0, 1), a2 + hstep, voffA);
;             PG8_WAIT_V(8); PG8_WAIT_L(0); PG8_BAR; PG8_MMA(0, 0, At, B0); PG8_MMA(0, 1, At, B1); PG8_BAR; PG8_SCHED;
;             PG8_LDA(At, 1, 1); PG8_STAGE(PG8_SB(1, 0), b3, voffB); PG8_STAGE(PG8_SB(1, 1), b3 + hstep, voffB); PG8_STAGE(PG8_SA(1, 0), a3, voffA);
;             PG8_WAIT_V(8); PG8_WAIT_L(0); PG8_BAR; PG8_MMA(1, 0, At, B0); PG8_MMA(1, 1, At, B1); PG8_BAR; PG8_SCHED;
	s_add_i32 s30, s51, s41
	v_lshl_add_u64 v[212:213], v[212:213], 0, s[12:13]
	s_mov_b32 m0, s30
	ds_read_b128 v[180:183], v155 offset:49152
	ds_read_b128 v[184:187], v155 offset:50176
	ds_read_b128 v[188:191], v155 offset:51200
	ds_read_b128 v[192:195], v155 offset:52224
	ds_read_b128 v[196:199], v155 offset:53248
	ds_read_b128 v[200:203], v155 offset:54272
	ds_read_b128 v[204:207], v155 offset:55296
	ds_read_b128 v[208:211], v155 offset:56320
	global_load_lds_dwordx4 v[212:213], off
	s_add_i32 m0, s30, 0x2000
	s_add_u32 s28, s28, 0x80080
	v_lshl_add_u64 v[212:213], v[214:215], 0, s[12:13]
	s_addc_u32 s29, s29, 0
	s_add_i32 s30, s52, s41
	global_load_lds_dwordx4 v[212:213], off
	v_lshl_add_u64 v[212:213], s[28:29], 0, v[0:1]
	s_mov_b32 m0, s30
	s_nop 0
	global_load_lds_dwordx4 v[212:213], off
	v_lshl_add_u64 v[212:213], s[28:29], 0, v[130:131]
	s_add_i32 m0, s30, 0x2000
	s_nop 0
	global_load_lds_dwordx4 v[212:213], off
	v_lshl_add_u64 v[212:213], v[216:217], 0, s[12:13]
	s_mov_b32 m0, s46
	s_nop 0
	global_load_lds_dwordx4 v[212:213], off
	v_lshl_add_u64 v[212:213], v[218:219], 0, s[12:13]
	s_mov_b32 m0, s47
	s_nop 0
	global_load_lds_dwordx4 v[212:213], off
	s_waitcnt vmcnt(8)
	s_waitcnt lgkmcnt(0)
	s_setprio 1
	s_barrier
	v_mfma_f32_16x16x32_bf16 v[62:65], v[140:143], v[180:183], v[62:65]
	v_mfma_f32_16x16x32_bf16 v[62:65], v[144:147], v[184:187], v[62:65]
	v_mfma_f32_16x16x32_bf16 v[58:61], v[156:159], v[180:183], v[58:61]
	v_mfma_f32_16x16x32_bf16 v[58:61], v[160:163], v[184:187], v[58:61]
	v_mfma_f32_16x16x32_bf16 v[42:45], v[156:159], v[188:191], v[42:45]
	v_mfma_f32_16x16x32_bf16 v[42:45], v[160:163], v[192:195], v[42:45]
	v_mfma_f32_16x16x32_bf16 v[46:49], v[140:143], v[188:191], v[46:49]
	v_mfma_f32_16x16x32_bf16 v[46:49], v[144:147], v[192:195], v[46:49]
	v_mfma_f32_16x16x32_bf16 v[30:33], v[140:143], v[196:199], v[30:33]
	v_mfma_f32_16x16x32_bf16 v[30:33], v[144:147], v[200:203], v[30:33]
	v_mfma_f32_16x16x32_bf16 v[26:29], v[156:159], v[196:199], v[26:29]
	v_mfma_f32_16x16x32_bf16 v[26:29], v[160:163], v[200:203], v[26:29]
	v_mfma_f32_16x16x32_bf16 v[10:13], v[156:159], v[204:207], v[10:13]
	v_mfma_f32_16x16x32_bf16 v[10:13], v[160:163], v[208:211], v[10:13]
	v_mfma_f32_16x16x32_bf16 v[14:17], v[140:143], v[204:207], v[14:17]
	v_mfma_f32_16x16x32_bf16 v[14:17], v[144:147], v[208:211], v[14:17]
	s_setprio 0
	s_setprio 1
	v_mfma_f32_16x16x32_bf16 v[54:57], v[164:167], v[180:183], v[54:57]
	v_mfma_f32_16x16x32_bf16 v[54:57], v[168:171], v[184:187], v[54:57]
	v_mfma_f32_16x16x32_bf16 v[50:53], v[172:175], v[180:183], v[50:53]
	v_mfma_f32_16x16x32_bf16 v[50:53], v[176:179], v[184:187], v[50:53]
	v_mfma_f32_16x16x32_bf16 v[34:37], v[172:175], v[188:191], v[34:37]
	v_mfma_f32_16x16x32_bf16 v[34:37], v[176:179], v[192:195], v[34:37]
	v_mfma_f32_16x16x32_bf16 v[38:41], v[164:167], v[188:191], v[38:41]
	v_mfma_f32_16x16x32_bf16 v[38:41], v[168:171], v[192:195], v[38:41]
	v_mfma_f32_16x16x32_bf16 v[22:25], v[164:167], v[196:199], v[22:25]
	v_mfma_f32_16x16x32_bf16 v[22:25], v[168:171], v[200:203], v[22:25]
	v_mfma_f32_16x16x32_bf16 v[18:21], v[172:175], v[196:199], v[18:21]
	v_mfma_f32_16x16x32_bf16 v[18:21], v[176:179], v[200:203], v[18:21]
	v_mfma_f32_16x16x32_bf16 v[2:5], v[172:175], v[204:207], v[2:5]
	v_mfma_f32_16x16x32_bf16 v[2:5], v[176:179], v[208:211], v[2:5]
	v_mfma_f32_16x16x32_bf16 v[6:9], v[164:167], v[204:207], v[6:9]
	v_mfma_f32_16x16x32_bf16 v[6:9], v[168:171], v[208:211], v[6:9]
	s_setprio 0
	s_barrier
	s_add_i32 s50, s50, 2
	s_add_u32 s26, s26, 0x100
	s_addc_u32 s27, s27, 0
	s_add_u32 s35, s35, 0x100
	s_addc_u32 s49, s49, 0
	s_cmp_gt_u32 s50, 29
	s_cbranch_scc0 .LBB0_924
	s_and_b64 vcc, exec, s[16:17]
	s_cbranch_vccz .LBB0_927
	s_barrier

; #define PG8_STAGE(bufoff, gbase, voff) do { _Pragma("unroll") for (int _i = 0; _i < 2; ++_i) \
;         __builtin_amdgcn_global_load_lds((const unsigned*)((const char*)(gbase) + (voff)[_i]), (LAS unsigned*)(lds + (bufoff) + ldsw + _i * 8192), 16, 0, 0); } while (0)
; #define PG8_LDA(dst, b, h) do { _Pragma("unroll") for (int m = 0; m < 4; ++m) _Pragma("unroll") for (int k = 0; k < 2; ++k) dst[m][k] = *(const LAS bf16x8*)(lds + PG8_SA(b, h) + aoff + m * 2048 + k * 1024); } while (0)
; #define PG8_LDB(dst, b, h) do { _Pragma("unroll") for (int n = 0; n < 2; ++n) _Pragma("unroll") for (int k = 0; k < 2; ++k) dst[n][k] = *(const LAS bf16x8*)(lds + PG8_SB(b, h) + boff + n * 2048 + k * 1024); } while (0)
; template <class Epi, class Sched, bool ALIGN_EPI = false, bool SP2 = false>
; __device__ __forceinline__ void gemm_phase(LAS unsigned char* lds, const Gemm g, const Sched& S, const Epi& E) {
;     ...
;         for (int t = 0; t < nt; t += 2) {
;             const bool last = (t == nt - 2);
;             const char* a1 = cA + (size_t)(t + 1) * kstep;
;             const char* a2 = last ? nA : cA + (size_t)(t + 2) * kstep; const char* b2 = last ? nB : cB + (size_t)(t + 2) * kstep;
;             const char* a3 = a2 + kstep; const char* b3 = b2 + kstep;
;             if (last && has_next) S.a_ready(nxt);
;             if constexpr (SP2) {
;             PG8_LDB(B0, 0, 0); PG8_LDB(B1, 0, 1); PG8_SCHED; PG8_LDA(At, 0, 0); PG8_STAGE(PG8_SA(1, 1), a1 + hstep, voffA);
;             PG8_WAIT_V(8); PG8_WAIT_L(0); PG8_BAR; PG8_MMA(0, 0, At, B0); PG8_MMA(0, 1, At, B1); PG8_BAR; PG8_SCHED;
;             PG8_LDA(At, 0, 1); PG8_STAGE(PG8_SB(0, 0), b2, voffB); PG8_STAGE(PG8_SB(0, 1), b2 + hstep, voffB); PG8_STAGE(PG8_SA(0, 0), a2, voffA);
;             PG8_WAIT_V(8); PG8_WAIT_L(0); PG8_BAR; PG8_MMA(1, 0, At, B0); PG8_MMA(1, 1, At, B1); PG8_BAR; PG8_SCHED;
;             PG8_LDB(B0, 1, 0); PG8_LDB(B1, 1, 1); PG8_SCHED; PG8_LDA(At, 1, 0); PG8_STAGE(PG8_SA(0, 1), a2 + hstep, voffA);
;             PG8_WAIT_V(8); PG8_WAIT_L(0); PG8_BAR; PG8_MMA(0, 0, At, B0); PG8_MMA(0, 1, At, B1); PG8_BAR; PG8_SCHED;
;             PG8_LDA(At, 1, 1); PG8_STAGE(PG8_SB(1, 0), b3, voffB); PG8_STAGE(PG8_SB(1, 1), b3 + hstep, voffB); PG8_STAGE(PG8_SA(1, 0), a3, voffA);
;             PG8_WAIT_V(8); PG8_WAIT_L(0); PG8_BAR; PG8_MMA(1, 0, At, B0); PG8_MMA(1, 1, At, B1); PG8_BAR; PG8_SCHED;
.LBB0_1007:
	s_add_u32 s24, s22, 0x100
	s_addc_u32 s25, s23, 0
	s_add_i32 s49, 0, 0x10000
	s_cmpk_eq_i32 s48, 0x54
	s_cselect_b32 s29, s1, s25
	s_cselect_b32 s28, s0, s24
	s_cselect_b32 s27, s21, s47
	s_cselect_b32 s26, s20, s46
	s_add_i32 s50, 0, 0x14000
	v_add_u32_e32 v126, s49, v247
	v_add_u32_e32 v158, s50, v247
	ds_read_b128 v[90:93], v126
	ds_read_b128 v[102:105], v126 offset:1024
	ds_read_b128 v[114:117], v126 offset:2048
	ds_read_b128 v[126:129], v126 offset:3072
	ds_read_b128 v[138:141], v158
	ds_read_b128 v[142:145], v158 offset:1024
	ds_read_b128 v[154:157], v158 offset:2048
	ds_read_b128 v[158:161], v158 offset:3072
	v_lshl_add_u64 v[204:205], s[22:23], 0, v[200:201]
	s_add_i32 m0, s8, 0xc000
	ds_read_b128 v[162:165], v249
	ds_read_b128 v[166:169], v249 offset:1024
	ds_read_b128 v[170:173], v249 offset:2048
	ds_read_b128 v[174:177], v249 offset:3072
	ds_read_b128 v[178:181], v249 offset:4096
	ds_read_b128 v[182:185], v249 offset:5120
	ds_read_b128 v[186:189], v249 offset:6144
	ds_read_b128 v[190:193], v249 offset:7168
	global_load_lds_dwordx4 v[204:205], off
	v_lshl_add_u64 v[204:205], s[22:23], 0, v[202:203]
	s_add_i32 m0, s8, 0xe000
	s_nop 0
	global_load_lds_dwordx4 v[204:205], off
	s_waitcnt vmcnt(8)
	s_waitcnt lgkmcnt(0)
	s_setprio 1
	s_barrier
	v_mfma_f32_16x16x32_bf16 v[150:153], v[90:93], v[162:165], v[150:153]
	v_mfma_f32_16x16x32_bf16 v[150:153], v[102:105], v[166:169], v[150:153]
	v_mfma_f32_16x16x32_bf16 v[146:149], v[114:117], v[162:165], v[146:149]
	v_mfma_f32_16x16x32_bf16 v[146:149], v[126:129], v[166:169], v[146:149]
	v_mfma_f32_16x16x32_bf16 v[118:121], v[114:117], v[170:173], v[118:121]
	v_mfma_f32_16x16x32_bf16 v[118:121], v[126:129], v[174:177], v[118:121]
	v_mfma_f32_16x16x32_bf16 v[122:125], v[90:93], v[170:173], v[122:125]
	v_mfma_f32_16x16x32_bf16 v[122:125], v[102:105], v[174:177], v[122:125]
	v_mfma_f32_16x16x32_bf16 v[98:101], v[90:93], v[178:181], v[98:101]
	v_mfma_f32_16x16x32_bf16 v[98:101], v[102:105], v[182:185], v[98:101]
	v_mfma_f32_16x16x32_bf16 v[94:97], v[114:117], v[178:181], v[94:97]
	v_mfma_f32_16x16x32_bf16 v[94:97], v[126:129], v[182:185], v[94:97]
	v_mfma_f32_16x16x32_bf16 v[74:77], v[114:117], v[186:189], v[74:77]
	v_mfma_f32_16x16x32_bf16 v[74:77], v[126:129], v[190:193], v[74:77]
	v_mfma_f32_16x16x32_bf16 v[78:81], v[90:93], v[186:189], v[78:81]
	v_mfma_f32_16x16x32_bf16 v[78:81], v[102:105], v[190:193], v[78:81]
	s_setprio 0
	s_setprio 1
	v_mfma_f32_16x16x32_bf16 v[134:137], v[138:141], v[162:165], v[134:137]
	v_mfma_f32_16x16x32_bf16 v[134:137], v[142:145], v[166:169], v[134:137]
	v_mfma_f32_16x16x32_bf16 v[130:133], v[154:157], v[162:165], v[130:133]
	v_mfma_f32_16x16x32_bf16 v[130:133], v[158:161], v[166:169], v[130:133]
	v_mfma_f32_16x16x32_bf16 v[106:109], v[154:157], v[170:173], v[106:109]
	v_mfma_f32_16x16x32_bf16 v[106:109], v[158:161], v[174:177], v[106:109]
	v_mfma_f32_16x16x32_bf16 v[110:113], v[138:141], v[170:173], v[110:113]
	v_mfma_f32_16x16x32_bf16 v[110:113], v[142:145], v[174:177], v[110:113]
	v_mfma_f32_16x16x32_bf16 v[86:89], v[138:141], v[178:181], v[86:89]
	v_mfma_f32_16x16x32_bf16 v[86:89], v[142:145], v[182:185], v[86:89]
	v_mfma_f32_16x16x32_bf16 v[82:85], v[154:157], v[178:181], v[82:85]
	v_mfma_f32_16x16x32_bf16 v[82:85], v[158:161], v[182:185], v[82:85]
	v_mfma_f32_16x16x32_bf16 v[66:69], v[154:157], v[186:189], v[66:69]
	v_mfma_f32_16x16x32_bf16 v[66:69], v[158:161], v[190:193], v[66:69]
	v_mfma_f32_16x16x32_bf16 v[70:73], v[138:141], v[186:189], v[70:73]
	v_mfma_f32_16x16x32_bf16 v[70:73], v[142:145], v[190:193], v[70:73]
	s_setprio 0
	s_barrier
	s_add_i32 s22, s49, s7
	v_lshl_add_u64 v[204:205], s[26:27], 0, v[0:1]
	s_mov_b32 m0, s22
	ds_read_b128 v[162:165], v249 offset:16384
	ds_read_b128 v[166:169], v249 offset:17408
	ds_read_b128 v[170:173], v249 offset:18432
	ds_read_b128 v[174:177], v249 offset:19456
	ds_read_b128 v[178:181], v249 offset:20480
	ds_read_b128 v[182:185], v249 offset:21504
	ds_read_b128 v[186:189], v249 offset:22528
	ds_read_b128 v[190:193], v249 offset:23552
	global_load_lds_dwordx4 v[204:205], off
	s_add_i32 m0, s22, 0x2000
	s_add_u32 s22, s26, 0x160000
	v_lshl_add_u64 v[206:207], s[26:27], 0, v[194:195]
	s_addc_u32 s23, s27, 0
	s_add_i32 s49, s50, s7
	global_load_lds_dwordx4 v[206:207], off
	v_lshl_add_u64 v[208:209], s[22:23], 0, v[0:1]
	s_mov_b32 m0, s49
	v_lshl_add_u64 v[210:211], s[28:29], 0, v[196:197]
	global_load_lds_dwordx4 v[208:209], off
	v_lshl_add_u64 v[208:209], s[22:23], 0, v[194:195]
	s_add_i32 m0, s49, 0x2000
	s_nop 0
	global_load_lds_dwordx4 v[208:209], off
	v_lshl_add_u64 v[208:209], s[28:29], 0, v[198:199]
	s_mov_b32 m0, s8
	s_nop 0
	global_load_lds_dwordx4 v[208:209], off
	s_mov_b32 m0, s9
	s_nop 0
	global_load_lds_dwordx4 v[210:211], off
	s_waitcnt vmcnt(8)
	s_waitcnt lgkmcnt(0)
	s_setprio 1
	s_barrier
; #define PG8_STAGE(bufoff, gbase, voff) do { _Pragma("unroll") for (int _i = 0; _i < 2; ++_i) \
;         __builtin_amdgcn_global_load_lds((const unsigned*)((const char*)(gbase) + (voff)[_i]), (LAS unsigned*)(lds + (bufoff) + ldsw + _i * 8192), 16, 0, 0); } while (0)
; #define PG8_LDA(dst, b, h) do { _Pragma("unroll") for (int m = 0; m < 4; ++m) _Pragma("unroll") for (int k = 0; k < 2; ++k) dst[m][k] = *(const LAS bf16x8*)(lds + PG8_SA(b, h) + aoff + m * 2048 + k * 1024); } while (0)
; #define PG8_LDB(dst, b, h) do { _Pragma("unroll") for (int n = 0; n < 2; ++n) _Pragma("unroll") for (int k = 0; k < 2; ++k) dst[n][k] = *(const LAS bf16x8*)(lds + PG8_SB(b, h) + boff + n * 2048 + k * 1024); } while (0)
; template <class Epi, class Sched, bool ALIGN_EPI = false, bool SP2 = false>
; __device__ __forceinline__ void gemm_phase(LAS unsigned char* lds, const Gemm g, const Sched& S, const Epi& E) {
;     ...
;         for (int t = 0; t < nt; t += 2) {
;             const bool last = (t == nt - 2);
;             const char* a1 = cA + (size_t)(t + 1) * kstep;
;             const char* a2 = last ? nA : cA + (size_t)(t + 2) * kstep; const char* b2 = last ? nB : cB + (size_t)(t + 2) * kstep;
;             const char* a3 = a2 + kstep; const char* b3 = b2 + kstep;
;             if (last && has_next) S.a_ready(nxt);
;             if constexpr (SP2) {
;             PG8_LDB(B0, 0, 0); PG8_LDB(B1, 0, 1); PG8_SCHED; PG8_LDA(At, 0, 0); PG8_STAGE(PG8_SA(1, 1), a1 + hstep, voffA);
;             PG8_WAIT_V(8); PG8_WAIT_L(0); PG8_BAR; PG8_MMA(0, 0, At, B0); PG8_MMA(0, 1, At, B1); PG8_BAR; PG8_SCHED;
;             PG8_LDA(At, 0, 1); PG8_STAGE(PG8_SB(0, 0), b2, voffB); PG8_STAGE(PG8_SB(0, 1), b2 + hstep, voffB); PG8_STAGE(PG8_SA(0, 0), a2, voffA);
;             PG8_WAIT_V(8); PG8_WAIT_L(0); PG8_BAR; PG8_MMA(1, 0, At, B0); PG8_MMA(1, 1, At, B1); PG8_BAR; PG8_SCHED;
;             PG8_LDB(B0, 1, 0); PG8_LDB(B1, 1, 1); PG8_SCHED; PG8_LDA(At, 1, 0); PG8_STAGE(PG8_SA(0, 1), a2 + hstep, voffA);
;             PG8_WAIT_V(8); PG8_WAIT_L(0); PG8_BAR; PG8_MMA(0, 0, At, B0); PG8_MMA(0, 1, At, B1); PG8_BAR; PG8_SCHED;
;             PG8_LDA(At, 1, 1); PG8_STAGE(PG8_SB(1, 0), b3, voffB); PG8_STAGE(PG8_SB(1, 1), b3 + hstep, voffB); PG8_STAGE(PG8_SA(1, 0), a3, voffA);
;             PG8_WAIT_V(8); PG8_WAIT_L(0); PG8_BAR; PG8_MMA(1, 0, At, B0); PG8_MMA(1, 1, At, B1); PG8_BAR; PG8_SCHED;
	v_mfma_f32_16x16x32_bf16 v[62:65], v[90:93], v[162:165], v[62:65]
	v_mfma_f32_16x16x32_bf16 v[62:65], v[102:105], v[166:169], v[62:65]
	v_mfma_f32_16x16x32_bf16 v[58:61], v[114:117], v[162:165], v[58:61]
	v_mfma_f32_16x16x32_bf16 v[58:61], v[126:129], v[166:169], v[58:61]
	v_mfma_f32_16x16x32_bf16 v[42:45], v[114:117], v[170:173], v[42:45]
	v_mfma_f32_16x16x32_bf16 v[42:45], v[126:129], v[174:177], v[42:45]
	v_mfma_f32_16x16x32_bf16 v[46:49], v[90:93], v[170:173], v[46:49]
	v_mfma_f32_16x16x32_bf16 v[46:49], v[102:105], v[174:177], v[46:49]
	v_mfma_f32_16x16x32_bf16 v[30:33], v[90:93], v[178:181], v[30:33]
	v_mfma_f32_16x16x32_bf16 v[30:33], v[102:105], v[182:185], v[30:33]
	v_mfma_f32_16x16x32_bf16 v[26:29], v[114:117], v[178:181], v[26:29]
	v_mfma_f32_16x16x32_bf16 v[26:29], v[126:129], v[182:185], v[26:29]
	v_mfma_f32_16x16x32_bf16 v[10:13], v[114:117], v[186:189], v[10:13]
	v_mfma_f32_16x16x32_bf16 v[10:13], v[126:129], v[190:193], v[10:13]
	v_mfma_f32_16x16x32_bf16 v[14:17], v[90:93], v[186:189], v[14:17]
	v_mfma_f32_16x16x32_bf16 v[14:17], v[102:105], v[190:193], v[14:17]
	s_setprio 0
	s_setprio 1
	v_mfma_f32_16x16x32_bf16 v[54:57], v[138:141], v[162:165], v[54:57]
	v_mfma_f32_16x16x32_bf16 v[54:57], v[142:145], v[166:169], v[54:57]
	v_mfma_f32_16x16x32_bf16 v[50:53], v[154:157], v[162:165], v[50:53]
	v_mfma_f32_16x16x32_bf16 v[50:53], v[158:161], v[166:169], v[50:53]
	v_mfma_f32_16x16x32_bf16 v[34:37], v[154:157], v[170:173], v[34:37]
	v_mfma_f32_16x16x32_bf16 v[34:37], v[158:161], v[174:177], v[34:37]
	v_mfma_f32_16x16x32_bf16 v[38:41], v[138:141], v[170:173], v[38:41]
	v_mfma_f32_16x16x32_bf16 v[38:41], v[142:145], v[174:177], v[38:41]
	v_mfma_f32_16x16x32_bf16 v[22:25], v[138:141], v[178:181], v[22:25]
	v_mfma_f32_16x16x32_bf16 v[22:25], v[142:145], v[182:185], v[22:25]
	v_mfma_f32_16x16x32_bf16 v[18:21], v[154:157], v[178:181], v[18:21]
	v_mfma_f32_16x16x32_bf16 v[18:21], v[158:161], v[182:185], v[18:21]
	v_mfma_f32_16x16x32_bf16 v[2:5], v[154:157], v[186:189], v[2:5]
	v_mfma_f32_16x16x32_bf16 v[2:5], v[158:161], v[190:193], v[2:5]
	v_mfma_f32_16x16x32_bf16 v[6:9], v[138:141], v[186:189], v[6:9]
	v_mfma_f32_16x16x32_bf16 v[6:9], v[142:145], v[190:193], v[6:9]
	s_setprio 0
	s_barrier
	s_add_i32 s49, 0, 0x18000
	s_add_i32 s50, 0, 0x1c000
	v_add_u32_e32 v126, s49, v247
	v_add_u32_e32 v158, s50, v247
	ds_read_b128 v[90:93], v126
	ds_read_b128 v[102:105], v126 offset:1024
	ds_read_b128 v[114:117], v126 offset:2048
	ds_read_b128 v[126:129], v126 offset:3072
	ds_read_b128 v[138:141], v158
	ds_read_b128 v[142:145], v158 offset:1024
	ds_read_b128 v[154:157], v158 offset:2048
	ds_read_b128 v[158:161], v158 offset:3072
	s_add_u32 s22, s28, 0x160000
	s_addc_u32 s23, s29, 0
	s_mov_b32 m0, s30
	v_lshl_add_u64 v[212:213], s[22:23], 0, v[198:199]
	ds_read_b128 v[162:165], v249 offset:32768
	ds_read_b128 v[166:169], v249 offset:33792
	ds_read_b128 v[170:173], v249 offset:34816
	ds_read_b128 v[174:177], v249 offset:35840
	ds_read_b128 v[178:181], v249 offset:36864
	ds_read_b128 v[182:185], v249 offset:37888
	ds_read_b128 v[186:189], v249 offset:38912
	ds_read_b128 v[190:193], v249 offset:39936
	global_load_lds_dwordx4 v[212:213], off
	v_lshl_add_u64 v[212:213], s[22:23], 0, v[196:197]
	s_mov_b32 m0, s31
	s_nop 0
	global_load_lds_dwordx4 v[212:213], off
	s_waitcnt vmcnt(8)
	s_waitcnt lgkmcnt(0)
	s_setprio 1
	s_barrier
	v_mfma_f32_16x16x32_bf16 v[150:153], v[90:93], v[162:165], v[150:153]
	v_mfma_f32_16x16x32_bf16 v[150:153], v[102:105], v[166:169], v[150:153]
	v_mfma_f32_16x16x32_bf16 v[146:149], v[114:117], v[162:165], v[146:149]
	v_mfma_f32_16x16x32_bf16 v[146:149], v[126:129], v[166:169], v[146:149]
	v_mfma_f32_16x16x32_bf16 v[118:121], v[114:117], v[170:173], v[118:121]
	v_mfma_f32_16x16x32_bf16 v[118:121], v[126:129], v[174:177], v[118:121]
	v_mfma_f32_16x16x32_bf16 v[122:125], v[90:93], v[170:173], v[122:125]
	v_mfma_f32_16x16x32_bf16 v[122:125], v[102:105], v[174:177], v[122:125]
	v_mfma_f32_16x16x32_bf16 v[98:101], v[90:93], v[178:181], v[98:101]
	v_mfma_f32_16x16x32_bf16 v[98:101], v[102:105], v[182:185], v[98:101]
	v_mfma_f32_16x16x32_bf16 v[94:97], v[114:117], v[178:181], v[94:97]
	v_mfma_f32_16x16x32_bf16 v[94:97], v[126:129], v[182:185], v[94:97]
	v_mfma_f32_16x16x32_bf16 v[74:77], v[114:117], v[186:189], v[74:77]
	v_mfma_f32_16x16x32_bf16 v[74:77], v[126:129], v[190:193], v[74:77]
	v_mfma_f32_16x16x32_bf16 v[78:81], v[90:93], v[186:189], v[78:81]
	v_mfma_f32_16x16x32_bf16 v[78:81], v[102:105], v[190:193], v[78:81]
	s_setprio 0
	s_setprio 1
	v_mfma_f32_16x16x32_bf16 v[134:137], v[138:141], v[162:165], v[134:137]
	v_mfma_f32_16x16x32_bf16 v[134:137], v[142:145], v[166:169], v[134:137]
	v_mfma_f32_16x16x32_bf16 v[130:133], v[154:157], v[162:165], v[130:133]
	v_mfma_f32_16x16x32_bf16 v[130:133], v[158:161], v[166:169], v[130:133]
	v_mfma_f32_16x16x32_bf16 v[106:109], v[154:157], v[170:173], v[106:109]
	v_mfma_f32_16x16x32_bf16 v[106:109], v[158:161], v[174:177], v[106:109]
	v_mfma_f32_16x16x32_bf16 v[110:113], v[138:141], v[170:173], v[110:113]
	v_mfma_f32_16x16x32_bf16 v[110:113], v[142:145], v[174:177], v[110:113]
	v_mfma_f32_16x16x32_bf16 v[86:89], v[138:141], v[178:181], v[86:89]
	v_mfma_f32_16x16x32_bf16 v[86:89], v[142:145], v[182:185], v[86:89]
	v_mfma_f32_16x16x32_bf16 v[82:85], v[154:157], v[178:181], v[82:85]
	v_mfma_f32_16x16x32_bf16 v[82:85], v[158:161], v[182:185], v[82:85]
	v_mfma_f32_16x16x32_bf16 v[66:69], v[154:157], v[186:189], v[66:69]
	v_mfma_f32_16x16x32_bf16 v[66:69], v[158:161], v[190:193], v[66:69]
	v_mfma_f32_16x16x32_bf16 v[70:73], v[138:141], v[186:189], v[70:73]
	v_mfma_f32_16x16x32_bf16 v[70:73], v[142:145], v[190:193], v[70:73]
	s_setprio 0
	s_barrier
; #define PG8_STAGE(bufoff, gbase, voff) do { _Pragma("unroll") for (int _i = 0; _i < 2; ++_i) \
;         __builtin_amdgcn_global_load_lds((const unsigned*)((const char*)(gbase) + (voff)[_i]), (LAS unsigned*)(lds + (bufoff) + ldsw + _i * 8192), 16, 0, 0); } while (0)
; #define PG8_LDA(dst, b, h) do { _Pragma("unroll") for (int m = 0; m < 4; ++m) _Pragma("unroll") for (int k = 0; k < 2; ++k) dst[m][k] = *(const LAS bf16x8*)(lds + PG8_SA(b, h) + aoff + m * 2048 + k * 1024); } while (0)
; #define PG8_LDB(dst, b, h) do { _Pragma("unroll") for (int n = 0; n < 2; ++n) _Pragma("unroll") for (int k = 0; k < 2; ++k) dst[n][k] = *(const LAS bf16x8*)(lds + PG8_SB(b, h) + boff + n * 2048 + k * 1024); } while (0)
; template <class Epi, class Sched, bool ALIGN_EPI = false, bool SP2 = false>
; __device__ __forceinline__ void gemm_phase(LAS unsigned char* lds, const Gemm g, const Sched& S, const Epi& E) {
;     ...
;         for (int t = 0; t < nt; t += 2) {
;             const bool last = (t == nt - 2);
;             const char* a1 = cA + (size_t)(t + 1) * kstep;
;             const char* a2 = last ? nA : cA + (size_t)(t + 2) * kstep; const char* b2 = last ? nB : cB + (size_t)(t + 2) * kstep;
;             const char* a3 = a2 + kstep; const char* b3 = b2 + kstep;
;             if (last && has_next) S.a_ready(nxt);
;             if constexpr (SP2) {
;             PG8_LDB(B0, 0, 0); PG8_LDB(B1, 0, 1); PG8_SCHED; PG8_LDA(At, 0, 0); PG8_STAGE(PG8_SA(1, 1), a1 + hstep, voffA);
;             PG8_WAIT_V(8); PG8_WAIT_L(0); PG8_BAR; PG8_MMA(0, 0, At, B0); PG8_MMA(0, 1, At, B1); PG8_BAR; PG8_SCHED;
;             PG8_LDA(At, 0, 1); PG8_STAGE(PG8_SB(0, 0), b2, voffB); PG8_STAGE(PG8_SB(0, 1), b2 + hstep, voffB); PG8_STAGE(PG8_SA(0, 0), a2, voffA);
;             PG8_WAIT_V(8); PG8_WAIT_L(0); PG8_BAR; PG8_MMA(1, 0, At, B0); PG8_MMA(1, 1, At, B1); PG8_BAR; PG8_SCHED;
;             PG8_LDB(B0, 1, 0); PG8_LDB(B1, 1, 1); PG8_SCHED; PG8_LDA(At, 1, 0); PG8_STAGE(PG8_SA(0, 1), a2 + hstep, voffA);
;             PG8_WAIT_V(8); PG8_WAIT_L(0); PG8_BAR; PG8_MMA(0, 0, At, B0); PG8_MMA(0, 1, At, B1); PG8_BAR; PG8_SCHED;
;             PG8_LDA(At, 1, 1); PG8_STAGE(PG8_SB(1, 0), b3, voffB); PG8_STAGE(PG8_SB(1, 1), b3 + hstep, voffB); PG8_STAGE(PG8_SA(1, 0), a3, voffA);
;             PG8_WAIT_V(8); PG8_WAIT_L(0); PG8_BAR; PG8_MMA(1, 0, At, B0); PG8_MMA(1, 1, At, B1); PG8_BAR; PG8_SCHED;
	s_add_i32 s22, s49, s7
	v_lshl_add_u64 v[204:205], v[204:205], 0, s[12:13]
	s_mov_b32 m0, s22
	ds_read_b128 v[162:165], v249 offset:49152
	ds_read_b128 v[166:169], v249 offset:50176
	ds_read_b128 v[170:173], v249 offset:51200
	ds_read_b128 v[174:177], v249 offset:52224
	ds_read_b128 v[178:181], v249 offset:53248
	ds_read_b128 v[182:185], v249 offset:54272
	ds_read_b128 v[186:189], v249 offset:55296
	ds_read_b128 v[190:193], v249 offset:56320
	global_load_lds_dwordx4 v[204:205], off
	s_add_i32 m0, s22, 0x2000
	s_add_u32 s22, s26, 0x160080
	v_lshl_add_u64 v[204:205], v[206:207], 0, s[12:13]
	s_addc_u32 s23, s27, 0
	s_add_i32 s26, s50, s7
	global_load_lds_dwordx4 v[204:205], off
	v_lshl_add_u64 v[204:205], s[22:23], 0, v[0:1]
	s_mov_b32 m0, s26
	s_nop 0
	global_load_lds_dwordx4 v[204:205], off
	v_lshl_add_u64 v[204:205], s[22:23], 0, v[194:195]
	s_add_i32 m0, s26, 0x2000
	s_nop 0
	global_load_lds_dwordx4 v[204:205], off
	v_lshl_add_u64 v[204:205], v[208:209], 0, s[12:13]
	s_mov_b32 m0, s35
	s_nop 0
	global_load_lds_dwordx4 v[204:205], off
	v_lshl_add_u64 v[204:205], v[210:211], 0, s[12:13]
	s_mov_b32 m0, s40
	s_nop 0
	global_load_lds_dwordx4 v[204:205], off
	s_waitcnt vmcnt(8)
	s_waitcnt lgkmcnt(0)
	s_setprio 1
	s_barrier
	v_mfma_f32_16x16x32_bf16 v[62:65], v[90:93], v[162:165], v[62:65]
	v_mfma_f32_16x16x32_bf16 v[62:65], v[102:105], v[166:169], v[62:65]
	v_mfma_f32_16x16x32_bf16 v[58:61], v[114:117], v[162:165], v[58:61]
	v_mfma_f32_16x16x32_bf16 v[58:61], v[126:129], v[166:169], v[58:61]
	v_mfma_f32_16x16x32_bf16 v[42:45], v[114:117], v[170:173], v[42:45]
	v_mfma_f32_16x16x32_bf16 v[42:45], v[126:129], v[174:177], v[42:45]
	v_mfma_f32_16x16x32_bf16 v[46:49], v[90:93], v[170:173], v[46:49]
	v_mfma_f32_16x16x32_bf16 v[46:49], v[102:105], v[174:177], v[46:49]
	v_mfma_f32_16x16x32_bf16 v[30:33], v[90:93], v[178:181], v[30:33]
	v_mfma_f32_16x16x32_bf16 v[30:33], v[102:105], v[182:185], v[30:33]
	v_mfma_f32_16x16x32_bf16 v[26:29], v[114:117], v[178:181], v[26:29]
	v_mfma_f32_16x16x32_bf16 v[26:29], v[126:129], v[182:185], v[26:29]
	v_mfma_f32_16x16x32_bf16 v[10:13], v[114:117], v[186:189], v[10:13]
	v_mfma_f32_16x16x32_bf16 v[10:13], v[126:129], v[190:193], v[10:13]
	v_mfma_f32_16x16x32_bf16 v[14:17], v[90:93], v[186:189], v[14:17]
	v_mfma_f32_16x16x32_bf16 v[14:17], v[102:105], v[190:193], v[14:17]
	s_setprio 0
	s_setprio 1
	v_mfma_f32_16x16x32_bf16 v[54:57], v[138:141], v[162:165], v[54:57]
	v_mfma_f32_16x16x32_bf16 v[54:57], v[142:145], v[166:169], v[54:57]
	v_mfma_f32_16x16x32_bf16 v[50:53], v[154:157], v[162:165], v[50:53]
	v_mfma_f32_16x16x32_bf16 v[50:53], v[158:161], v[166:169], v[50:53]
	v_mfma_f32_16x16x32_bf16 v[34:37], v[154:157], v[170:173], v[34:37]
	v_mfma_f32_16x16x32_bf16 v[34:37], v[158:161], v[174:177], v[34:37]
	v_mfma_f32_16x16x32_bf16 v[38:41], v[138:141], v[170:173], v[38:41]
	v_mfma_f32_16x16x32_bf16 v[38:41], v[142:145], v[174:177], v[38:41]
	v_mfma_f32_16x16x32_bf16 v[22:25], v[138:141], v[178:181], v[22:25]
	v_mfma_f32_16x16x32_bf16 v[22:25], v[142:145], v[182:185], v[22:25]
	v_mfma_f32_16x16x32_bf16 v[18:21], v[154:157], v[178:181], v[18:21]
	v_mfma_f32_16x16x32_bf16 v[18:21], v[158:161], v[182:185], v[18:21]
	v_mfma_f32_16x16x32_bf16 v[2:5], v[154:157], v[186:189], v[2:5]
	v_mfma_f32_16x16x32_bf16 v[2:5], v[158:161], v[190:193], v[2:5]
	v_mfma_f32_16x16x32_bf16 v[6:9], v[138:141], v[186:189], v[6:9]
	v_mfma_f32_16x16x32_bf16 v[6:9], v[142:145], v[190:193], v[6:9]
	s_setprio 0
	s_barrier
	s_add_i32 s48, s48, 2
	s_add_u32 s46, s46, 0x100
	s_addc_u32 s47, s47, 0
	s_cmpk_gt_u32 s48, 0x55
	s_mov_b64 s[22:23], s[24:25]
	s_cbranch_scc0 .LBB0_1007
	s_and_b64 vcc, exec, s[18:19]
	s_cbranch_vccz .LBB0_1010
	s_barrier
